# P4 tile loads parallel, P1 loop spurious vmcnt0 removed, P2 and P0 item order reversed for half the WGs
# speedup vs baseline: 1.1837x; 1.0567x over previous
; #define LAS __attribute__((address_space(3)))
; __device__ __forceinline__ unsigned pk_bf16(float lo, float hi) { unsigned r; asm volatile("v_cvt_pk_bf16_f32 %0, %1, %2" : "=v"(r) : "v"(lo), "v"(hi)); return r; }
; __device__ __forceinline__ float bf_lo(unsigned u) { return __uint_as_float(u << 16); }
; __device__ __forceinline__ float bf_hi(unsigned u) { return __uint_as_float(u & 0xffff0000u); }
; __device__ __forceinline__ int launder(int v) { asm volatile("" : "+v"(v)); return v; }
; __device__ __forceinline__ float lg2gamma(int h) { return log1pf(-exp2f(-5.0f - (float)h)) * 1.4426950408889634f; }
; template <bool SCALE>
; __device__ __forceinline__ void load_tile(LAS unsigned char* dst, const bf16_t* src, size_t ld, int nvalid, float lg, int tid) {
; #pragma unroll
;     for (int i = 0; i < 8; ++i) {
;         const int idx = i * 512 + tid, row = idx >> 5, ch = idx & 31;
;         u32x4 v = (u32x4){0u, 0u, 0u, 0u};
;         if (row < nvalid) {
;             v = *(const u32x4*)(src + (size_t)row * ld + ch * 8);
;             if (SCALE) { const float f = exp2f(lg * (float)(nvalid - 1 - row));
;                 v.x = pk_bf16(bf_lo(v.x) * f, bf_hi(v.x) * f); v.y = pk_bf16(bf_lo(v.y) * f, bf_hi(v.y) * f);
;                 v.z = pk_bf16(bf_lo(v.z) * f, bf_hi(v.z) * f); v.w = pk_bf16(bf_lo(v.w) * f, bf_hi(v.w) * f); }
;         }
;         *(LAS u32x4*)(dst + img_off(row, ch * 8)) = v;
;     }
; }
; __device__ void ret_out_unit(const Params& p, int l, int unit, LAS unsigned char* lds, const int tid_in) {
;     const int tid = launder(tid_in); const int wid = __builtin_amdgcn_readfirstlane(tid >> 6);
;     int b, h, c, n, R0, slot; chunk_geom(unit, b, h, c, n, R0, slot);
;     const float lg = lg2gamma(h);
;     const bf16_t* zb = (const bf16_t*)(pws(p) + OFF_ZB) + (size_t)R0 * ZW + h * 256;
;     LAS unsigned char* regA = lds; LAS unsigned char* regB = lds + 65536;
;     load_tile<false>(regA, zb + ZC_Q, ZW, n, 0.f, tid);
;     load_tile<false>(regB, zb + ZC_K, ZW, n, 0.f, tid);
;     __syncthreads();
;     const int jb = (wid & 3) * 32, ib = (wid >> 2) * 64;
;     u32x2 pk[2][4];
;     {
;         const int lane = launder(tid) & 63, g = lane >> 4, lc = lane & 15;
;         f32x4 sc[2][4];
; #pragma unroll
;         for (int i = 0; i < 2; ++i)
; #pragma unroll
;             for (int j = 0; j < 4; ++j) sc[i][j] = (f32x4){0.f, 0.f, 0.f, 0.f};
.LBB0_300:
	s_and_b32 s0, s85, 15
	s_add_i32 s0, s0, 1
	s_cmp_lt_i32 s85, 32
	s_cselect_b32 s28, 0, s0
	s_lshl_b32 s0, s28, 7
	s_addk_i32 s0, 0xff90
	s_cmp_lt_i32 s85, 32
	s_mov_b64 s[44:45], s[72:73]
	s_cselect_b32 s73, 16, 0x80
	s_cselect_b32 s0, 0, s0
	s_sub_i32 s1, s85, 32
	s_lshr_b32 s1, s1, 4
	s_cmp_lt_i32 s85, 32
	s_cselect_b32 s29, s85, s1
	s_cmp_gt_i32 s85, 31
	s_cselect_b64 s[26:27], -1, 0
	s_lshr_b32 s1, s29, 3
	s_mulk_i32 s1, 0x810
	s_add_i32 s72, s1, s0
	s_addk_i32 s72, 0x400
	v_mov_b32_e32 v124, v244
	s_and_b32 s24, s29, 7
	s_mul_i32 s1, s72, 0x7000
	v_readlane_b32 s6, v253, 19
	s_mul_hi_i32 s0, s72, 0x7000
	v_readlane_b32 s7, v253, 20
	s_add_u32 s1, s6, s1
	s_addc_u32 s6, s7, s0
	s_lshl_b32 s0, s24, 9
	s_waitcnt vmcnt(0)
	v_lshlrev_b32_e32 v3, 3, v124
	s_add_u32 s0, s1, s0
	v_and_b32_e32 v0, 0xf8, v3
	s_addc_u32 s1, s6, 0
	v_lshlrev_b32_e32 v0, 1, v0
	v_lshl_add_u64 v[4:5], s[0:1], 0, v[0:1]
	s_mov_b64 s[6:7], 0x1000
	v_ashrrev_i32_e32 v74, 5, v124
	s_mov_b64 s[46:47], s[2:3]
	s_mov_b64 s[2:3], s[4:5]
	s_mov_b64 s[4:5], s[66:67]
	v_readfirstlane_b32 s80, v124
	v_add_u32_e32 v76, 0x10, v74
	v_add_u32_e32 v78, 0x20, v74
	v_add_u32_e32 v80, 0x30, v74
	v_add_u32_e32 v82, 0x40, v74
	v_add_u32_e32 v84, 0x50, v74
	v_add_u32_e32 v86, 0x60, v74
	v_add_u32_e32 v88, 0x70, v74
	v_cmp_gt_i32_e64 s[6:7], s73, v74
	v_cmp_gt_i32_e64 s[8:9], s73, v76
	v_cmp_gt_i32_e64 s[10:11], s73, v78
	v_cmp_gt_i32_e64 s[12:13], s73, v80
	v_cmp_gt_i32_e64 s[14:15], s73, v82
	v_cmp_gt_i32_e64 s[16:17], s73, v84
	v_cmp_gt_i32_e64 s[18:19], s73, v86
	v_cmp_gt_i32_e64 s[20:21], s73, v88
	v_mul_u32_u24_e32 v3, 0x7000, v74
	v_add_u32_e32 v3, v3, v0
	v_and_b32_e32 v4, 3, v74
	v_bfe_u32 v5, v74, 2, 2
	v_lshl_or_b32 v4, v4, 2, v5
	v_and_b32_e32 v5, 15, v124
	v_xor_b32_e32 v4, v4, v5
	v_lshlrev_b32_e32 v4, 4, v4
	v_lshl_add_u32 v4, v74, 8, v4
	v_bfe_u32 v5, v124, 4, 1
	v_lshl_add_u32 v5, v5, 15, v4
	v_add_u32_e32 v125, 0x10000, v5
	v_add_u32_e32 v126, 0x11000, v5
	v_add_u32_e32 v127, 0x12000, v5
	v_add_u32_e32 v128, 0x13000, v5
	v_add_u32_e32 v129, 0x14000, v5
	v_add_u32_e32 v130, 0x15000, v5
	v_add_u32_e32 v131, 0x16000, v5
	v_add_u32_e32 v132, 0x17000, v5
	s_add_u32 s22, s0, 0x1000
	s_addc_u32 s23, s1, 0
	s_add_u32 s30, s0, 0x2000
	s_addc_u32 s31, s1, 0
	s_cmp_eq_u32 s73, 16
	s_cbranch_scc1 .Lro_small
	global_load_dwordx4 v[8:11], v3, s[22:23]
	s_add_u32 s22, s22, 0x70000
	s_addc_u32 s23, s23, 0
	global_load_dwordx4 v[12:15], v3, s[22:23]
	s_add_u32 s22, s22, 0x70000
	s_addc_u32 s23, s23, 0
	global_load_dwordx4 v[16:19], v3, s[22:23]
	s_add_u32 s22, s22, 0x70000
	s_addc_u32 s23, s23, 0
	global_load_dwordx4 v[20:23], v3, s[22:23]
	s_add_u32 s22, s22, 0x70000
	s_addc_u32 s23, s23, 0
	global_load_dwordx4 v[24:27], v3, s[22:23]
	s_add_u32 s22, s22, 0x70000
	s_addc_u32 s23, s23, 0
	global_load_dwordx4 v[28:31], v3, s[22:23]
	s_add_u32 s22, s22, 0x70000
	s_addc_u32 s23, s23, 0
	global_load_dwordx4 v[32:35], v3, s[22:23]
	s_add_u32 s22, s22, 0x70000
	s_addc_u32 s23, s23, 0
	global_load_dwordx4 v[36:39], v3, s[22:23]
	global_load_dwordx4 v[40:43], v3, s[30:31]
	s_add_u32 s30, s30, 0x70000
	s_addc_u32 s31, s31, 0
	global_load_dwordx4 v[44:47], v3, s[30:31]
	s_add_u32 s30, s30, 0x70000
	s_addc_u32 s31, s31, 0
	global_load_dwordx4 v[48:51], v3, s[30:31]
	s_add_u32 s30, s30, 0x70000
	s_addc_u32 s31, s31, 0
	global_load_dwordx4 v[52:55], v3, s[30:31]
	s_add_u32 s30, s30, 0x70000
	s_addc_u32 s31, s31, 0
	global_load_dwordx4 v[56:59], v3, s[30:31]
	s_add_u32 s30, s30, 0x70000
	s_addc_u32 s31, s31, 0
	global_load_dwordx4 v[60:63], v3, s[30:31]
	s_add_u32 s30, s30, 0x70000
	s_addc_u32 s31, s31, 0
	global_load_dwordx4 v[64:67], v3, s[30:31]
	s_add_u32 s30, s30, 0x70000
	s_addc_u32 s31, s31, 0
	global_load_dwordx4 v[68:71], v3, s[30:31]
	s_waitcnt vmcnt(15)
	ds_write_b128 v5, v[8:11] offset:0
	s_waitcnt vmcnt(14)
	ds_write_b128 v5, v[12:15] offset:4096
	s_waitcnt vmcnt(13)
	ds_write_b128 v5, v[16:19] offset:8192
	s_waitcnt vmcnt(12)
	ds_write_b128 v5, v[20:23] offset:12288
	s_waitcnt vmcnt(11)
	ds_write_b128 v5, v[24:27] offset:16384
	s_waitcnt vmcnt(10)
	ds_write_b128 v5, v[28:31] offset:20480
	s_waitcnt vmcnt(9)
	ds_write_b128 v5, v[32:35] offset:24576
	s_waitcnt vmcnt(8)
	ds_write_b128 v5, v[36:39] offset:28672
	s_waitcnt vmcnt(7)
	ds_write_b128 v125, v[40:43] offset:0
	s_waitcnt vmcnt(6)
	ds_write_b128 v125, v[44:47] offset:4096
	s_waitcnt vmcnt(5)
	ds_write_b128 v125, v[48:51] offset:8192
	s_waitcnt vmcnt(4)
	ds_write_b128 v125, v[52:55] offset:12288
	s_waitcnt vmcnt(3)
	ds_write_b128 v125, v[56:59] offset:16384
	s_waitcnt vmcnt(2)
	ds_write_b128 v125, v[60:63] offset:20480
	s_waitcnt vmcnt(1)
	ds_write_b128 v125, v[64:67] offset:24576
	s_waitcnt vmcnt(0)
	ds_write_b128 v125, v[68:71] offset:28672
	s_branch .Lro_join
.Lro_small:
	global_load_dwordx4 v[8:11], v3, s[22:23]
	global_load_dwordx4 v[40:43], v3, s[30:31]
	v_mov_b32_e32 v12, 0
	v_mov_b32_e32 v13, 0
	v_mov_b32_e32 v14, 0
	v_mov_b32_e32 v15, 0
	ds_write_b128 v5, v[12:15] offset:4096
	ds_write_b128 v125, v[12:15] offset:4096
	ds_write_b128 v5, v[12:15] offset:8192
	ds_write_b128 v125, v[12:15] offset:8192
	ds_write_b128 v5, v[12:15] offset:12288
	ds_write_b128 v125, v[12:15] offset:12288
	ds_write_b128 v5, v[12:15] offset:16384
	ds_write_b128 v125, v[12:15] offset:16384
	ds_write_b128 v5, v[12:15] offset:20480
	ds_write_b128 v125, v[12:15] offset:20480
	ds_write_b128 v5, v[12:15] offset:24576
	ds_write_b128 v125, v[12:15] offset:24576
	ds_write_b128 v5, v[12:15] offset:28672
	ds_write_b128 v125, v[12:15] offset:28672
	s_waitcnt vmcnt(1)
	ds_write_b128 v5, v[8:11]
	s_waitcnt vmcnt(0)
	ds_write_b128 v125, v[40:43]
.Lro_join:
	v_mov_b32_e32 v6, 0
	s_add_i32 s64, 0, 0x10000
	s_ashr_i32 s66, s80, 6
	s_lshl_b32 s22, s66, 5
	s_ashr_i32 s65, s80, 2
	v_mov_b32_e32 v2, v124
	s_waitcnt lgkmcnt(0)
	s_barrier
	s_and_b32 s61, s22, 0x60
	s_and_b32 s62, s65, 0xffffffc0
	v_and_b32_e32 v3, 15, v2
	v_lshlrev_b32_e32 v4, 2, v2
	v_bfe_u32 v5, v2, 2, 2
	s_ashr_i32 s79, s72, 31
	s_lshl_b32 s33, s24, 8
	v_lshrrev_b32_e32 v35, 2, v2
	v_and_or_b32 v36, v4, 12, v5
	v_or_b32_e32 v34, s62, v3
	v_or_b32_e32 v37, s61, v3
	v_bfe_u32 v38, v2, 4, 2
	s_mov_b32 s22, 0
	v_mov_b32_e32 v7, v6
	v_mov_b32_e32 v8, v6
	v_mov_b32_e32 v9, v6
	v_mov_b32_e32 v14, v6
	v_mov_b32_e32 v15, v6
	v_mov_b32_e32 v16, v6
	v_mov_b32_e32 v17, v6
	v_mov_b32_e32 v18, v6
	v_mov_b32_e32 v19, v6
	v_mov_b32_e32 v20, v6
	v_mov_b32_e32 v21, v6
	v_mov_b32_e32 v22, v6
	v_mov_b32_e32 v23, v6
	v_mov_b32_e32 v24, v6
	v_mov_b32_e32 v25, v6
	v_mov_b32_e32 v26, v6
	v_mov_b32_e32 v27, v6
	v_mov_b32_e32 v28, v6
	v_mov_b32_e32 v29, v6
	v_mov_b32_e32 v30, v6
	v_mov_b32_e32 v31, v6
	v_mov_b32_e32 v32, v6
	v_mov_b32_e32 v33, v6
	v_mov_b32_e32 v10, v6
	v_mov_b32_e32 v11, v6
	v_mov_b32_e32 v12, v6
	v_mov_b32_e32 v13, v6
	v_mov_b32_e32 v2, v6
	v_mov_b32_e32 v3, v6
	v_mov_b32_e32 v4, v6
	v_mov_b32_e32 v5, v6

; #define LAS __attribute__((address_space(3)))
; __device__ __forceinline__ unsigned pk_bf16(float lo, float hi) { unsigned r; asm volatile("v_cvt_pk_bf16_f32 %0, %1, %2" : "=v"(r) : "v"(lo), "v"(hi)); return r; }
; __device__ __forceinline__ float bf_lo(unsigned u) { return __uint_as_float(u << 16); }
; __device__ __forceinline__ float bf_hi(unsigned u) { return __uint_as_float(u & 0xffff0000u); }
; template <bool SCALE>
; __device__ __forceinline__ void load_tile(LAS unsigned char* dst, const bf16_t* src, size_t ld, int nvalid, float lg, int tid) {
; #pragma unroll
;     for (int i = 0; i < 8; ++i) {
;         const int idx = i * 512 + tid, row = idx >> 5, ch = idx & 31;
;         u32x4 v = (u32x4){0u, 0u, 0u, 0u};
;         if (row < nvalid) {
;             v = *(const u32x4*)(src + (size_t)row * ld + ch * 8);
;             if (SCALE) { const float f = exp2f(lg * (float)(nvalid - 1 - row));
;                 v.x = pk_bf16(bf_lo(v.x) * f, bf_hi(v.x) * f); v.y = pk_bf16(bf_lo(v.y) * f, bf_hi(v.y) * f);
;                 v.z = pk_bf16(bf_lo(v.z) * f, bf_hi(v.z) * f); v.w = pk_bf16(bf_lo(v.w) * f, bf_hi(v.w) * f); }
;         }
;         *(LAS u32x4*)(dst + img_off(row, ch * 8)) = v;
;     }
; }
; __device__ void ret_out_unit(const Params& p, int l, int unit, LAS unsigned char* lds, const int tid_in) {
;     ...
;         for (int half = 0; half < 2; ++half) {
;             __syncthreads();
;             load_tile<false>(regB, sb + (size_t)half * 128 * 256, 256, 128, 0.f, tid);
;             __syncthreads();
.LBB0_336:
	v_lshl_add_u64 v[72:73], s[90:91], 1, v[106:107]
	s_barrier
	v_lshl_add_u64 v[152:153], v[72:73], 0, v[108:109]
	global_load_dwordx4 v[152:155], v[152:153], off
	v_lshl_add_u64 v[156:157], v[72:73], 0, v[110:111]
	global_load_dwordx4 v[156:159], v[156:157], off
	v_lshl_add_u64 v[160:161], v[72:73], 0, v[112:113]
	global_load_dwordx4 v[160:163], v[160:161], off
	v_lshl_add_u64 v[164:165], v[72:73], 0, v[114:115]
	global_load_dwordx4 v[164:167], v[164:165], off
	v_lshl_add_u64 v[168:169], v[72:73], 0, v[116:117]
	global_load_dwordx4 v[168:171], v[168:169], off
	v_lshl_add_u64 v[172:173], v[72:73], 0, v[118:119]
	global_load_dwordx4 v[172:175], v[172:173], off
	v_lshl_add_u64 v[176:177], v[72:73], 0, v[120:121]
	global_load_dwordx4 v[176:179], v[176:177], off
	v_lshl_add_u64 v[180:181], v[72:73], 0, v[122:123]
	global_load_dwordx4 v[180:183], v[180:181], off
	s_xor_b64 vcc, s[40:41], -1
	v_add_u32_e32 v146, s90, v75
	s_mov_b32 s40, 0
	v_mov_b32_e32 v147, v77
	s_waitcnt vmcnt(7)
	ds_write_b128 v125, v[152:155]
	s_waitcnt vmcnt(6)
	ds_write_b128 v126, v[156:159]
	s_waitcnt vmcnt(5)
	ds_write_b128 v127, v[160:163]
	s_waitcnt vmcnt(4)
	ds_write_b128 v128, v[164:167]
	s_waitcnt vmcnt(3)
	ds_write_b128 v129, v[168:171]
	s_waitcnt vmcnt(2)
	ds_write_b128 v130, v[172:175]
	s_waitcnt vmcnt(1)
	ds_write_b128 v131, v[176:179]
	s_waitcnt vmcnt(0)
	ds_write_b128 v132, v[180:183]
	s_waitcnt lgkmcnt(0)
	s_barrier

; #define LAS __attribute__((address_space(3)))
; __device__ __forceinline__ int launder(int v) { asm volatile("" : "+v"(v)); return v; }
; __device__ void ret_out_unit(const Params& p, int l, int unit, LAS unsigned char* lds, const int tid_in) {
;     ...
;     { const int lane = launder(tid) & 63, g = lane >> 4, lc = lane & 15;
; #pragma unroll
;     for (int i = 0; i < 2; ++i)
; #pragma unroll
;         for (int j = 0; j < 4; ++j) *(LAS u32x2*)(regA + img_off(ib + j * 16 + lc, jb + i * 16 + 4 * g)) = pk[i][j]; }
;     load_tile<false>(regB, zb + ZC_V, ZW, n, 0.f, tid);
;     __syncthreads();
;     const int ksmax = (ib2 + 31) >> 5;
;     { const int lane = launder(tid) & 63;
; #pragma unroll 1
;     for (int ks = 0; ks <= ksmax; ++ks) {
;         bf16x8 a[2];
; #pragma unroll
;         for (int i = 0; i < 2; ++i) a[i] = frag_direct(regA, ib2 + i * 16, ks * 32, lane);
; #pragma unroll
;         for (int j = 0; j < 8; ++j) { const bf16x8 bs = frag_tr(regB, ks * 32, eb + j * 16, lane);
; #pragma unroll
;             for (int i = 0; i < 2; ++i) acc[i][j] = __builtin_amdgcn_mfma_f32_16x16x32_bf16(a[i], bs, acc[i][j], 0, 0, 0); }
;     } }
.LBB0_357:
	v_mov_b32_e32 v66, v124
	s_barrier
	s_mov_b64 s[22:23], 0x3000
	v_lshrrev_b32_e32 v68, 2, v66
	v_lshlrev_b32_e32 v69, 2, v66
	v_and_or_b32 v68, v68, 8, s61
	v_and_b32_e32 v69, 12, v69
	v_bfe_u32 v70, v66, 2, 2
	v_and_or_b32 v67, v66, 15, s62
	v_or_b32_e32 v71, v69, v70
	v_lshrrev_b32_e32 v66, 1, v66
	v_lshrrev_b32_e32 v68, 3, v68
	v_and_b32_e32 v66, 8, v66
	v_bitop3_b32 v69, v68, v69, v70 bitop3:0x1e
	v_bitop3_b32 v68, v68, v71, 2 bitop3:0x36
	v_add_u32_e32 v66, 0, v66
	v_lshlrev_b32_e32 v69, 4, v69
	v_lshlrev_b32_e32 v67, 8, v67
	v_lshlrev_b32_e32 v68, 4, v68
	v_add3_u32 v69, v66, v69, v67
	v_add3_u32 v66, v66, v68, v67
	ds_write2st64_b64 v69, v[90:91], v[92:93] offset1:8
	ds_write2st64_b64 v69, v[94:95], v[96:97] offset0:16 offset1:24
	ds_write2st64_b64 v66, v[98:99], v[100:101] offset1:8
	ds_write2st64_b64 v66, v[102:103], v[104:105] offset0:16 offset1:24
	v_lshl_add_u64 v[66:67], s[0:1], 0, v[0:1]
	v_lshl_add_u64 v[72:73], v[66:67], 0, s[22:23]
	v_mov_b32_e32 v152, 0
	v_mov_b32_e32 v153, 0
	v_mov_b32_e32 v154, 0
	v_mov_b32_e32 v155, 0
	s_and_saveexec_b64 s[22:23], s[6:7]
	s_cbranch_execz .Lro_vskip0
	v_mad_i64_i32 v[152:153], vcc, v74, s74, v[72:73]
	global_load_dwordx4 v[152:155], v[152:153], off
.Lro_vskip0:
	s_or_b64 exec, exec, s[22:23]
	v_mov_b32_e32 v156, 0
	v_mov_b32_e32 v157, 0
	v_mov_b32_e32 v158, 0
	v_mov_b32_e32 v159, 0
	s_and_saveexec_b64 s[22:23], s[8:9]
	s_cbranch_execz .Lro_vskip1
	v_mad_i64_i32 v[156:157], vcc, v76, s74, v[72:73]
	global_load_dwordx4 v[156:159], v[156:157], off
.Lro_vskip1:
	s_or_b64 exec, exec, s[22:23]
	v_mov_b32_e32 v160, 0
	v_mov_b32_e32 v161, 0
	v_mov_b32_e32 v162, 0
	v_mov_b32_e32 v163, 0
	s_and_saveexec_b64 s[22:23], s[10:11]
	s_cbranch_execz .Lro_vskip2
	v_mad_i64_i32 v[160:161], vcc, v78, s74, v[72:73]
	global_load_dwordx4 v[160:163], v[160:161], off
.Lro_vskip2:
	s_or_b64 exec, exec, s[22:23]
	v_mov_b32_e32 v164, 0
	v_mov_b32_e32 v165, 0
	v_mov_b32_e32 v166, 0
	v_mov_b32_e32 v167, 0
	s_and_saveexec_b64 s[22:23], s[12:13]
	s_cbranch_execz .Lro_vskip3
	v_mad_i64_i32 v[164:165], vcc, v80, s74, v[72:73]
	global_load_dwordx4 v[164:167], v[164:165], off
.Lro_vskip3:
	s_or_b64 exec, exec, s[22:23]
	v_mov_b32_e32 v168, 0
	v_mov_b32_e32 v169, 0
	v_mov_b32_e32 v170, 0
	v_mov_b32_e32 v171, 0
	s_and_saveexec_b64 s[22:23], s[14:15]
	s_cbranch_execz .Lro_vskip4
	v_mad_i64_i32 v[168:169], vcc, v82, s74, v[72:73]
	global_load_dwordx4 v[168:171], v[168:169], off
.Lro_vskip4:
	s_or_b64 exec, exec, s[22:23]
	v_mov_b32_e32 v172, 0
	v_mov_b32_e32 v173, 0
	v_mov_b32_e32 v174, 0
	v_mov_b32_e32 v175, 0
	s_and_saveexec_b64 s[22:23], s[16:17]
	s_cbranch_execz .Lro_vskip5
	v_mad_i64_i32 v[172:173], vcc, v84, s74, v[72:73]
	global_load_dwordx4 v[172:175], v[172:173], off
.Lro_vskip5:
	s_or_b64 exec, exec, s[22:23]
	v_mov_b32_e32 v176, 0
	v_mov_b32_e32 v177, 0
	v_mov_b32_e32 v178, 0
	v_mov_b32_e32 v179, 0
	s_and_saveexec_b64 s[22:23], s[18:19]
	s_cbranch_execz .Lro_vskip6
	v_mad_i64_i32 v[176:177], vcc, v86, s74, v[72:73]
	global_load_dwordx4 v[176:179], v[176:177], off
.Lro_vskip6:
	s_or_b64 exec, exec, s[22:23]
	v_mov_b32_e32 v180, 0
	v_mov_b32_e32 v181, 0
	v_mov_b32_e32 v182, 0
	v_mov_b32_e32 v183, 0
	s_and_saveexec_b64 s[22:23], s[20:21]
	s_cbranch_execz .Lro_vskip7
	v_mad_i64_i32 v[180:181], vcc, v88, s74, v[72:73]
	global_load_dwordx4 v[180:183], v[180:181], off
.Lro_vskip7:
	s_or_b64 exec, exec, s[22:23]
	s_ashr_i32 s6, s80, 7
	v_mov_b32_e32 v85, v124
	s_cmp_eq_u32 s73, 16
	s_cbranch_scc0 .Lro_vfull
	s_waitcnt vmcnt(0)
.Lro_vfull:
	s_waitcnt vmcnt(7)
	ds_write_b128 v125, v[152:155]
	s_waitcnt vmcnt(6)
	ds_write_b128 v126, v[156:159]
	s_waitcnt vmcnt(5)
	ds_write_b128 v127, v[160:163]
	s_waitcnt vmcnt(4)
	ds_write_b128 v128, v[164:167]
	s_waitcnt vmcnt(3)
	ds_write_b128 v129, v[168:171]
	s_waitcnt vmcnt(2)
	ds_write_b128 v130, v[172:175]
	s_waitcnt vmcnt(1)
	ds_write_b128 v131, v[176:179]
	s_waitcnt vmcnt(0)
	ds_write_b128 v132, v[180:183]
	s_cmp_lt_i32 s6, 0
	s_waitcnt lgkmcnt(0)
	s_barrier
	s_cbranch_scc1 .LBB0_376
	v_bfe_u32 v86, v85, 2, 2
	v_lshrrev_b32_e32 v67, 3, v85
	v_lshlrev_b32_e32 v69, 2, v86
	v_and_b32_e32 v70, 2, v67
	v_lshrrev_b32_e32 v68, 1, v85
	v_or_b32_e32 v71, v69, v70
	v_bfe_u32 v87, v85, 1, 1
	v_and_b32_e32 v78, 24, v68
	v_bitop3_b32 v77, v71, v68, 1 bitop3:0x72
	v_or_b32_e32 v68, 2, v87
	v_bitop3_b32 v84, v69, v68, v70 bitop3:0x36
	v_bitop3_b32 v76, v71, v68, 1 bitop3:0x36
	v_or_b32_e32 v68, 4, v87
	v_bitop3_b32 v83, v69, v68, v70 bitop3:0x36
	v_bitop3_b32 v75, v71, v68, 1 bitop3:0x36
	v_or_b32_e32 v68, 6, v87
	v_bitop3_b32 v82, v69, v68, v70 bitop3:0x36
	v_bitop3_b32 v74, v71, v68, 1 bitop3:0x36
	v_or_b32_e32 v68, 8, v87
	v_bitop3_b32 v81, v69, v68, v70 bitop3:0x36
	v_bitop3_b32 v73, v71, v68, 1 bitop3:0x36
	v_or_b32_e32 v68, 10, v87
	s_lshl_b32 s7, s80, 9
	v_bitop3_b32 v80, v69, v68, v70 bitop3:0x36
	v_bitop3_b32 v72, v71, v68, 1 bitop3:0x36
	v_or_b32_e32 v68, 12, v87
	s_and_b32 s7, s7, 0x8000
	v_lshlrev_b32_e32 v66, 2, v85
	v_bitop3_b32 v79, v69, v68, v70 bitop3:0x36
	v_bitop3_b32 v88, v71, v68, 1 bitop3:0x36
	v_or_b32_e32 v68, 14, v87
	v_lshl_or_b32 v90, v86, 8, s7
	v_add_u32_e32 v78, s60, v78
	v_and_or_b32 v0, v85, 15, s65
	v_and_or_b32 v66, v66, 12, v86
	v_lshlrev_b32_e32 v67, 3, v85
	v_bitop3_b32 v89, v69, v68, v70 bitop3:0x36
	v_bitop3_b32 v69, v71, v68, 1 bitop3:0x36
	v_bfe_u32 v68, v85, 4, 2
	v_lshl_or_b32 v71, v88, 4, v90
	v_add_lshl_u32 v88, v78, v86, 8
	v_mul_u32_u24_e32 v86, 0x140, v86
	v_lshlrev_b32_e32 v85, 1, v85
	v_or_b32_e32 v86, s7, v86
	v_and_b32_e32 v85, 32, v85
	v_lshlrev_b32_e32 v87, 4, v87
	v_and_b32_e32 v67, 8, v67
	v_lshl_or_b32 v69, v69, 4, v90
	v_readlane_b32 s8, v254, 31
	v_lshl_or_b32 v72, v72, 4, v90
	v_lshl_or_b32 v73, v73, 4, v90
	v_lshl_or_b32 v74, v74, 4, v90
	v_lshl_or_b32 v75, v75, 4, v90
	v_lshl_or_b32 v76, v76, 4, v90
	v_lshl_or_b32 v77, v77, 4, v90
	v_lshl_or_b32 v78, v89, 4, v88
	v_lshl_or_b32 v79, v79, 4, v88
	v_lshl_or_b32 v80, v80, 4, v88
	v_lshl_or_b32 v81, v81, 4, v88
	v_lshl_or_b32 v82, v82, 4, v88
	v_lshl_or_b32 v83, v83, 4, v88
	v_lshl_or_b32 v84, v84, 4, v88
	v_or3_b32 v85, v86, v85, v87
	s_add_i32 s6, s6, 1
	v_add_u32_e32 v69, s8, v69
	v_lshl_or_b32 v70, v68, 11, v67
	v_add_u32_e32 v71, s8, v71
	v_add_u32_e32 v72, s8, v72
	v_add_u32_e32 v73, s8, v73
	v_add_u32_e32 v74, s8, v74
	v_add_u32_e32 v75, s8, v75
	v_add_u32_e32 v76, s8, v76
	v_add_u32_e32 v77, s8, v77
	v_add_u32_e32 v78, s64, v78
	v_add_u32_e32 v79, s64, v79
	v_add_u32_e32 v80, s64, v80
	v_add_u32_e32 v81, s64, v81
	v_add_u32_e32 v82, s64, v82
	v_add_u32_e32 v83, s64, v83
	v_add_u32_e32 v84, s64, v84
	v_add_u32_e32 v85, s64, v85
	s_mov_b32 s7, 0

; __device__ __forceinline__ void run_phase(const Params& p, int ph, LAS unsigned char* lds, const int tid, const int bid) {
;     ...
;         for (int it = bid; it < 1024 + 544 + 580; it += G) {
;             if (it < 1024) sample_ret_unit(p, l, it, lds, tid);
;             else if (it < 1568) kv_unit(p, it - 1024, lds, tid);
;             else pool_item(p, l, it - 1568, tid);
;         }
.LBB0_447:
	s_andn2_b64 vcc, exec, s[0:1]
	s_cbranch_vccnz .LBB0_582
	v_readlane_b32 s0, v254, 48
	s_and_b32 s0, 0xffff, s0
	s_cmp_gt_i32 s0, 0
	s_mov_b64 s[0:1], -1
	s_cbranch_scc0 .LBB0_547
	s_cmpk_gt_i32 s82, 0x863
	s_cbranch_scc1 .LBB0_546
	v_readlane_b32 s0, v254, 46
	v_readlane_b32 s1, v254, 47
	s_mov_b32 s1, s91
	v_readlane_b32 s8, v253, 57
	s_lshl_b64 s[22:23], s[0:1], 7
	s_lshl_b64 s[24:25], s[0:1], 2
	s_lshl_b64 s[26:27], s[0:1], 10
	s_mov_b32 s6, s0
	s_lshl_b64 s[0:1], s[0:1], 13
	v_readlane_b32 s10, v253, 59
	v_readlane_b32 s11, v253, 60
	s_add_u32 s34, s10, s0
	v_writelane_b32 v254, s6, 46
	s_addc_u32 s35, s11, s1
	s_mov_b32 s38, s82
	s_cmpk_lg_u32 s42, 0x100
	s_cbranch_scc1 .Lp2_fwd0
	s_bitcmp1_b32 s82, 3
	s_cbranch_scc0 .Lp2_fwd0
	s_sub_i32 s0, 0x863, s82
	s_andn2_b32 s0, s0, 0xff
	s_add_i32 s38, s82, s0
.Lp2_fwd0:
	s_lshl_b32 s0, s38, 4
	v_writelane_b32 v254, s7, 47
	s_add_i32 s36, s0, 0xffff9e00
	s_add_i32 s37, s0, 0xffff9dff
	v_readlane_b32 s9, v253, 58
	s_branch .LBB0_452
.LBB0_451:
	v_readlane_b32 s0, v254, 16
	s_cmpk_lg_u32 s42, 0x100
	s_cbranch_scc1 .Lp2_fwd1
	s_bitcmp1_b32 s82, 3
	s_cbranch_scc0 .Lp2_fwd1
	s_sub_i32 s38, s38, s42
	s_sub_i32 s36, s36, s0
	s_sub_i32 s37, s37, s0
	s_cmp_lt_i32 s38, 0
	s_cbranch_scc1 .LBB0_546
	s_branch .LBB0_452
.Lp2_fwd1:
	s_add_i32 s38, s38, s42
	s_add_i32 s36, s36, s0
	s_add_i32 s37, s37, s0
	s_cmpk_gt_i32 s38, 0x863
	s_cbranch_scc1 .LBB0_546

; #define LAS __attribute__((address_space(3)))
; __device__ __forceinline__ int launder(int v) { asm volatile("" : "+v"(v)); return v; }
; __device__ __forceinline__ float lg2gamma(int h) { return log1pf(-exp2f(-5.0f - (float)h)) * 1.4426950408889634f; }
; __device__ void kv_unit(const Params& p, int unit, LAS unsigned char* lds, const int tid_in) {
;     const int tid = launder(tid_in); const int wid = __builtin_amdgcn_readfirstlane(tid >> 6);
;     int b, h, c, n, R0, slot; chunk_geom(unit, b, h, c, n, R0, slot);
;     const float lg = lg2gamma(h);
;     const bf16_t* zb = (const bf16_t*)(pws(p) + OFF_ZB) + (size_t)R0 * ZW + h * 256;
;     LAS unsigned char* regA = lds; LAS unsigned char* regB = lds + 65536;
;     load_tile<true>(regA, zb + ZC_K, ZW, n, lg, tid);
;     load_tile<false>(regB, zb + ZC_V, ZW, n, 0.f, tid);
;     __syncthreads();
.LBB0_484:
	s_mov_b64 s[0:1], 0
	s_and_b64 vcc, exec, s[6:7]
	s_mov_b64 s[6:7], 0
	s_cbranch_vccz .LBB0_522
	s_and_b32 s7, s38, 15
	s_add_i32 s6, s38, 0xfffffc00
	s_add_i32 s7, s7, 1
	s_cmp_lt_u32 s6, 32
	s_cselect_b32 s40, 0, s7
	s_lshl_b32 s7, s40, 7
	s_addk_i32 s7, 0xff90
	s_cmp_lt_u32 s6, 32
	s_cselect_b32 s33, 16, 0x80
	s_cselect_b32 s7, 0, s7
	s_add_i32 s8, s38, 0xfffffbe0
	s_lshr_b32 s8, s8, 4
	s_cmp_lt_u32 s6, 32
	s_cselect_b32 s41, s6, s8
	s_and_b32 s8, s41, 7
	v_cvt_f32_ubyte0_e32 v0, s8
	v_sub_f32_e32 v0, 0xc0a00000, v0
	v_cmp_gt_f32_e32 vcc, s75, v0
	s_lshr_b32 s6, s41, 3
	s_mulk_i32 s6, 0x810
	s_waitcnt vmcnt(0)
	v_cndmask_b32_e32 v2, 0, v237, vcc
	v_add_f32_e32 v0, v0, v2
	s_add_i32 s6, s6, s7
	v_exp_f32_e32 v0, v0
	s_add_i32 s9, s6, 0x400
	s_and_b64 s[6:7], vcc, exec
	s_cselect_b32 s6, 0xffffffc0, 0
	v_ldexp_f32 v0, v0, s6
	v_sub_f32_e32 v4, 1.0, v0
	v_add_f32_e32 v2, -1.0, v4
	v_sub_f32_e32 v3, v2, v4
	v_add_f32_e32 v3, 1.0, v3
	v_sub_f32_e64 v2, -v0, v2
	v_add_f32_e32 v5, v2, v3
	v_frexp_mant_f32_e32 v6, v4
	v_cvt_f64_f32_e32 v[2:3], v4
	s_mov_b32 s6, 0x3f2aaaab
	v_frexp_exp_i32_f64_e32 v2, v[2:3]
	v_cmp_gt_f32_e32 vcc, s6, v6
	s_mov_b32 s6, 0x3f317218
	v_readlane_b32 s10, v253, 19
	v_subbrev_co_u32_e32 v2, vcc, 0, v2, vcc
	v_sub_u32_e32 v3, 0, v2
	v_ldexp_f32 v4, v4, v3
	v_ldexp_f32 v3, v5, v3
	v_add_f32_e32 v5, -1.0, v4
	v_add_f32_e32 v8, 1.0, v4
	v_add_f32_e32 v6, 1.0, v5
	v_add_f32_e32 v9, -1.0, v8
	v_sub_f32_e32 v6, v4, v6
	v_sub_f32_e32 v4, v4, v9
	v_add_f32_e32 v6, v3, v6
	v_add_f32_e32 v3, v3, v4
	v_add_f32_e32 v4, v8, v3
	v_rcp_f32_e32 v9, v4
	v_add_f32_e32 v7, v5, v6
	v_sub_f32_e32 v5, v7, v5
	v_sub_f32_e32 v5, v6, v5
	v_sub_f32_e32 v6, v4, v8
	v_sub_f32_e32 v3, v3, v6
	v_mul_f32_e32 v6, v7, v9
	v_mul_f32_e32 v8, v4, v6
	v_fma_f32 v10, v6, v4, -v8
	v_fmac_f32_e32 v10, v6, v3
	v_add_f32_e32 v11, v8, v10
	v_sub_f32_e32 v12, v7, v11
	v_sub_f32_e32 v7, v7, v12
	v_sub_f32_e32 v8, v11, v8
	v_sub_f32_e32 v7, v7, v11
	v_add_f32_e32 v5, v5, v7
	v_sub_f32_e32 v7, v8, v10
	v_add_f32_e32 v5, v7, v5
	v_add_f32_e32 v7, v12, v5
	v_mul_f32_e32 v8, v9, v7
	v_mul_f32_e32 v10, v4, v8
	v_fma_f32 v4, v8, v4, -v10
	v_fmac_f32_e32 v4, v8, v3
	v_sub_f32_e32 v3, v12, v7
	v_add_f32_e32 v3, v5, v3
	v_add_f32_e32 v5, v10, v4
	v_sub_f32_e32 v11, v7, v5
	v_sub_f32_e32 v7, v7, v11
	v_sub_f32_e32 v10, v5, v10
	v_sub_f32_e32 v5, v7, v5
	v_add_f32_e32 v3, v3, v5
	v_sub_f32_e32 v4, v10, v4
	v_cvt_f32_i32_e32 v2, v2
	v_add_f32_e32 v3, v4, v3
	v_add_f32_e32 v4, v6, v8
	v_add_f32_e32 v3, v11, v3
	v_sub_f32_e32 v5, v4, v6
	v_mul_f32_e32 v3, v9, v3
	v_sub_f32_e32 v5, v8, v5
	v_add_f32_e32 v3, v5, v3
	v_mul_f32_e32 v8, 0x3f317218, v2
	v_add_f32_e32 v5, v4, v3
	v_fma_f32 v9, v2, s6, -v8
	v_mul_f32_e32 v6, v5, v5
	v_fmac_f32_e32 v9, 0xb102e308, v2
	v_sub_f32_e32 v2, v5, v4
	v_fmamk_f32 v7, v6, 0x3e9b6dac, v234
	v_sub_f32_e32 v2, v3, v2
	v_add_f32_e32 v3, v8, v9
	v_fmaak_f32 v7, v6, v7, 0x3f2aaada
	v_sub_f32_e32 v4, v3, v8
	v_ldexp_f32 v8, v5, 1
	v_mul_f32_e32 v5, v5, v6
	v_mul_f32_e32 v5, v5, v7
	v_add_f32_e32 v6, v8, v5
	v_sub_f32_e32 v7, v6, v8
	v_ldexp_f32 v2, v2, 1
	v_sub_f32_e32 v5, v5, v7
	v_add_f32_e32 v2, v2, v5
	v_add_f32_e32 v5, v6, v2
	v_sub_f32_e32 v6, v5, v6
	v_sub_f32_e32 v2, v2, v6
	v_add_f32_e32 v6, v3, v5
	v_sub_f32_e32 v7, v6, v3
	v_sub_f32_e32 v8, v6, v7
	v_sub_f32_e32 v4, v9, v4
	v_sub_f32_e32 v3, v3, v8
	v_sub_f32_e32 v5, v5, v7
	v_add_f32_e32 v3, v5, v3
	v_add_f32_e32 v5, v4, v2
	v_sub_f32_e32 v7, v5, v4
	v_sub_f32_e32 v8, v5, v7
	v_sub_f32_e32 v4, v4, v8
	v_sub_f32_e32 v2, v2, v7
	v_add_f32_e32 v3, v5, v3
	v_add_f32_e32 v2, v2, v4
	v_add_f32_e32 v4, v6, v3
	v_sub_f32_e32 v5, v4, v6
	v_sub_f32_e32 v3, v3, v5
	v_add_f32_e32 v2, v2, v3
	v_add_f32_e32 v2, v4, v2
	v_cmp_nlt_f32_e32 vcc, 1.0, v0
	s_mov_b32 s6, 0x33800000
	v_mov_b32_e32 v34, v244
	v_cndmask_b32_e32 v2, v238, v2, vcc
	v_cmp_neq_f32_e32 vcc, 1.0, v0
	v_readlane_b32 s11, v253, 20
	v_mov_b32_e32 v6, 0
	v_cndmask_b32_e32 v2, v239, v2, vcc
	v_cmp_gt_f32_e32 vcc, s6, v0
	s_mul_hi_u32 s6, s9, 0x7000
	s_mulk_i32 s9, 0x7000
	s_add_u32 s7, s10, s9
	v_cndmask_b32_e64 v0, v2, -v0, vcc
	s_addc_u32 s6, s11, s6
	s_lshl_b32 s8, s8, 9
	v_lshlrev_b32_e32 v3, 3, v34
	v_mul_f32_e32 v12, 0x3fb8aa3b, v0
	s_add_u32 s28, s7, s8
	v_and_b32_e32 v0, 0xf8, v3
	s_addc_u32 s29, s6, 0
	v_lshlrev_b32_e32 v0, 1, v0
	v_lshl_add_u64 v[4:5], s[28:29], 0, v[0:1]
	s_mov_b64 s[6:7], 0x2000
	v_ashrrev_i32_e32 v10, 5, v34
	v_readfirstlane_b32 s39, v34
	v_mul_u32_u24_e32 v3, 0x7000, v10
	v_and_b32_e32 v4, 3, v10
	v_bfe_u32 v5, v10, 2, 2
	v_lshl_or_b32 v4, v4, 2, v5
	v_and_b32_e32 v5, 15, v34
	v_xor_b32_e32 v4, v4, v5
	v_lshlrev_b32_e32 v4, 4, v4
	v_lshl_add_u32 v4, v10, 8, v4
	v_bfe_u32 v5, v34, 4, 1
	v_lshl_add_u32 v2, v5, 15, v4
	v_add_u32_e32 v3, v3, v0
	v_add_u32_e32 v5, 0x10000, v2
	s_add_u32 s6, s28, 0x2000
	s_addc_u32 s7, s29, 0
	s_add_u32 s8, s28, 0x3000
	s_addc_u32 s9, s29, 0
	s_add_i32 s10, s33, -1
	v_sub_u32_e32 v6, s10, v10
	s_cmp_eq_u32 s33, 16
	s_cbranch_scc1 .Lkv_small
; #define LAS __attribute__((address_space(3)))
; __device__ __forceinline__ unsigned pk_bf16(float lo, float hi) { unsigned r; asm volatile("v_cvt_pk_bf16_f32 %0, %1, %2" : "=v"(r) : "v"(lo), "v"(hi)); return r; }
; __device__ __forceinline__ float bf_lo(unsigned u) { return __uint_as_float(u << 16); }
; __device__ __forceinline__ float bf_hi(unsigned u) { return __uint_as_float(u & 0xffff0000u); }
; template <bool SCALE>
; __device__ __forceinline__ void load_tile(LAS unsigned char* dst, const bf16_t* src, size_t ld, int nvalid, float lg, int tid) {
; #pragma unroll
;     for (int i = 0; i < 8; ++i) {
;         const int idx = i * 512 + tid, row = idx >> 5, ch = idx & 31;
;         u32x4 v = (u32x4){0u, 0u, 0u, 0u};
;         if (row < nvalid) {
;             v = *(const u32x4*)(src + (size_t)row * ld + ch * 8);
;             if (SCALE) { const float f = exp2f(lg * (float)(nvalid - 1 - row));
;                 v.x = pk_bf16(bf_lo(v.x) * f, bf_hi(v.x) * f); v.y = pk_bf16(bf_lo(v.y) * f, bf_hi(v.y) * f);
;                 v.z = pk_bf16(bf_lo(v.z) * f, bf_hi(v.z) * f); v.w = pk_bf16(bf_lo(v.w) * f, bf_hi(v.w) * f); }
;         }
;         *(LAS u32x4*)(dst + img_off(row, ch * 8)) = v;
;     }
; }
	global_load_dwordx4 v[64:67], v3, s[6:7]
	s_add_u32 s6, s6, 0x70000
	s_addc_u32 s7, s7, 0
	global_load_dwordx4 v[68:71], v3, s[6:7]
	s_add_u32 s6, s6, 0x70000
	s_addc_u32 s7, s7, 0
	global_load_dwordx4 v[72:75], v3, s[6:7]
	s_add_u32 s6, s6, 0x70000
	s_addc_u32 s7, s7, 0
	global_load_dwordx4 v[76:79], v3, s[6:7]
	s_add_u32 s6, s6, 0x70000
	s_addc_u32 s7, s7, 0
	global_load_dwordx4 v[80:83], v3, s[6:7]
	s_add_u32 s6, s6, 0x70000
	s_addc_u32 s7, s7, 0
	global_load_dwordx4 v[84:87], v3, s[6:7]
	s_add_u32 s6, s6, 0x70000
	s_addc_u32 s7, s7, 0
	global_load_dwordx4 v[88:91], v3, s[6:7]
	s_add_u32 s6, s6, 0x70000
	s_addc_u32 s7, s7, 0
	global_load_dwordx4 v[92:95], v3, s[6:7]
	global_load_dwordx4 v[96:99], v3, s[8:9]
	s_add_u32 s8, s8, 0x70000
	s_addc_u32 s9, s9, 0
	global_load_dwordx4 v[100:103], v3, s[8:9]
	s_add_u32 s8, s8, 0x70000
	s_addc_u32 s9, s9, 0
	global_load_dwordx4 v[104:107], v3, s[8:9]
	s_add_u32 s8, s8, 0x70000
	s_addc_u32 s9, s9, 0
	global_load_dwordx4 v[108:111], v3, s[8:9]
	s_add_u32 s8, s8, 0x70000
	s_addc_u32 s9, s9, 0
	global_load_dwordx4 v[112:115], v3, s[8:9]
	s_add_u32 s8, s8, 0x70000
	s_addc_u32 s9, s9, 0
	global_load_dwordx4 v[116:119], v3, s[8:9]
	s_add_u32 s8, s8, 0x70000
	s_addc_u32 s9, s9, 0
	global_load_dwordx4 v[120:123], v3, s[8:9]
	s_add_u32 s8, s8, 0x70000
	s_addc_u32 s9, s9, 0
	global_load_dwordx4 v[124:127], v3, s[8:9]
	v_mov_b32_e32 v7, v6
	v_cvt_f32_i32_e32 v7, v7
	v_mul_f32_e32 v7, v12, v7
	v_exp_f32_e32 v16, v7
	v_subrev_u32_e32 v7, 16, v6
	v_cvt_f32_i32_e32 v7, v7
	v_mul_f32_e32 v7, v12, v7
	v_exp_f32_e32 v17, v7
	v_subrev_u32_e32 v7, 32, v6
	v_cvt_f32_i32_e32 v7, v7
	v_mul_f32_e32 v7, v12, v7
	v_exp_f32_e32 v18, v7
	v_subrev_u32_e32 v7, 48, v6
	v_cvt_f32_i32_e32 v7, v7
	v_mul_f32_e32 v7, v12, v7
	v_exp_f32_e32 v19, v7
	v_subrev_u32_e32 v7, 64, v6
	v_cvt_f32_i32_e32 v7, v7
	v_mul_f32_e32 v7, v12, v7
	v_exp_f32_e32 v20, v7
	v_subrev_u32_e32 v7, 80, v6
	v_cvt_f32_i32_e32 v7, v7
	v_mul_f32_e32 v7, v12, v7
	v_exp_f32_e32 v21, v7
	v_subrev_u32_e32 v7, 96, v6
	v_cvt_f32_i32_e32 v7, v7
	v_mul_f32_e32 v7, v12, v7
	v_exp_f32_e32 v22, v7
	v_subrev_u32_e32 v7, 112, v6
	v_cvt_f32_i32_e32 v7, v7
	v_mul_f32_e32 v7, v12, v7
	v_exp_f32_e32 v23, v7
	s_nop 0
	s_waitcnt vmcnt(15)
	v_lshlrev_b32_e32 v24, 16, v64
	v_and_b32_e32 v64, 0xffff0000, v64
	v_lshlrev_b32_e32 v25, 16, v65
	v_and_b32_e32 v65, 0xffff0000, v65
	v_lshlrev_b32_e32 v26, 16, v66
	v_and_b32_e32 v66, 0xffff0000, v66
	v_lshlrev_b32_e32 v27, 16, v67
	v_and_b32_e32 v67, 0xffff0000, v67
	v_mul_f32_e32 v24, v16, v24
	v_mul_f32_e32 v64, v16, v64
	v_mul_f32_e32 v25, v16, v25
	v_mul_f32_e32 v65, v16, v65
	v_mul_f32_e32 v26, v16, v26
	v_mul_f32_e32 v66, v16, v66
	v_mul_f32_e32 v27, v16, v27
	v_mul_f32_e32 v67, v16, v67
	v_cvt_pk_bf16_f32 v64, v24, v64
	v_cvt_pk_bf16_f32 v65, v25, v65
	v_cvt_pk_bf16_f32 v66, v26, v66
	v_cvt_pk_bf16_f32 v67, v27, v67
	ds_write_b128 v2, v[64:67] offset:0
	s_waitcnt vmcnt(14)
	v_lshlrev_b32_e32 v24, 16, v68
	v_and_b32_e32 v68, 0xffff0000, v68
	v_lshlrev_b32_e32 v25, 16, v69
	v_and_b32_e32 v69, 0xffff0000, v69
	v_lshlrev_b32_e32 v26, 16, v70
	v_and_b32_e32 v70, 0xffff0000, v70
	v_lshlrev_b32_e32 v27, 16, v71
	v_and_b32_e32 v71, 0xffff0000, v71
	v_mul_f32_e32 v24, v17, v24
	v_mul_f32_e32 v68, v17, v68
	v_mul_f32_e32 v25, v17, v25
	v_mul_f32_e32 v69, v17, v69
	v_mul_f32_e32 v26, v17, v26
	v_mul_f32_e32 v70, v17, v70
	v_mul_f32_e32 v27, v17, v27
	v_mul_f32_e32 v71, v17, v71
	v_cvt_pk_bf16_f32 v68, v24, v68
	v_cvt_pk_bf16_f32 v69, v25, v69
	v_cvt_pk_bf16_f32 v70, v26, v70
	v_cvt_pk_bf16_f32 v71, v27, v71
	ds_write_b128 v2, v[68:71] offset:4096
	s_waitcnt vmcnt(13)
	v_lshlrev_b32_e32 v24, 16, v72
	v_and_b32_e32 v72, 0xffff0000, v72
	v_lshlrev_b32_e32 v25, 16, v73
	v_and_b32_e32 v73, 0xffff0000, v73
	v_lshlrev_b32_e32 v26, 16, v74
	v_and_b32_e32 v74, 0xffff0000, v74
	v_lshlrev_b32_e32 v27, 16, v75
	v_and_b32_e32 v75, 0xffff0000, v75
	v_mul_f32_e32 v24, v18, v24
	v_mul_f32_e32 v72, v18, v72
	v_mul_f32_e32 v25, v18, v25
	v_mul_f32_e32 v73, v18, v73
	v_mul_f32_e32 v26, v18, v26
	v_mul_f32_e32 v74, v18, v74
	v_mul_f32_e32 v27, v18, v27
	v_mul_f32_e32 v75, v18, v75
	v_cvt_pk_bf16_f32 v72, v24, v72
	v_cvt_pk_bf16_f32 v73, v25, v73
	v_cvt_pk_bf16_f32 v74, v26, v74
	v_cvt_pk_bf16_f32 v75, v27, v75
	ds_write_b128 v2, v[72:75] offset:8192
	s_waitcnt vmcnt(12)
	v_lshlrev_b32_e32 v24, 16, v76
	v_and_b32_e32 v76, 0xffff0000, v76
	v_lshlrev_b32_e32 v25, 16, v77
	v_and_b32_e32 v77, 0xffff0000, v77
	v_lshlrev_b32_e32 v26, 16, v78
	v_and_b32_e32 v78, 0xffff0000, v78
	v_lshlrev_b32_e32 v27, 16, v79
	v_and_b32_e32 v79, 0xffff0000, v79
	v_mul_f32_e32 v24, v19, v24
	v_mul_f32_e32 v76, v19, v76
	v_mul_f32_e32 v25, v19, v25
	v_mul_f32_e32 v77, v19, v77
	v_mul_f32_e32 v26, v19, v26
	v_mul_f32_e32 v78, v19, v78
	v_mul_f32_e32 v27, v19, v27
	v_mul_f32_e32 v79, v19, v79
	v_cvt_pk_bf16_f32 v76, v24, v76
	v_cvt_pk_bf16_f32 v77, v25, v77
	v_cvt_pk_bf16_f32 v78, v26, v78
	v_cvt_pk_bf16_f32 v79, v27, v79
	ds_write_b128 v2, v[76:79] offset:12288
	s_waitcnt vmcnt(11)
; #define LAS __attribute__((address_space(3)))
; __device__ __forceinline__ unsigned pk_bf16(float lo, float hi) { unsigned r; asm volatile("v_cvt_pk_bf16_f32 %0, %1, %2" : "=v"(r) : "v"(lo), "v"(hi)); return r; }
; __device__ __forceinline__ float bf_lo(unsigned u) { return __uint_as_float(u << 16); }
; __device__ __forceinline__ float bf_hi(unsigned u) { return __uint_as_float(u & 0xffff0000u); }
; template <bool SCALE>
; __device__ __forceinline__ void load_tile(LAS unsigned char* dst, const bf16_t* src, size_t ld, int nvalid, float lg, int tid) {
; #pragma unroll
;     for (int i = 0; i < 8; ++i) {
;         const int idx = i * 512 + tid, row = idx >> 5, ch = idx & 31;
;         u32x4 v = (u32x4){0u, 0u, 0u, 0u};
;         if (row < nvalid) {
;             v = *(const u32x4*)(src + (size_t)row * ld + ch * 8);
;             if (SCALE) { const float f = exp2f(lg * (float)(nvalid - 1 - row));
;                 v.x = pk_bf16(bf_lo(v.x) * f, bf_hi(v.x) * f); v.y = pk_bf16(bf_lo(v.y) * f, bf_hi(v.y) * f);
;                 v.z = pk_bf16(bf_lo(v.z) * f, bf_hi(v.z) * f); v.w = pk_bf16(bf_lo(v.w) * f, bf_hi(v.w) * f); }
;         }
;         *(LAS u32x4*)(dst + img_off(row, ch * 8)) = v;
;     }
; }
; __device__ void kv_unit(const Params& p, int unit, LAS unsigned char* lds, const int tid_in) {
;     ...
;     const int db = (wid >> 1) * 64, ebase = (wid & 1) * 128;
;     float* kv = (float*)(pws(p) + OFF_KV) + (size_t)slot * 65536;
;     const int nks = n >> 5 ? n >> 5 : 1;
	v_lshlrev_b32_e32 v24, 16, v80
	v_and_b32_e32 v80, 0xffff0000, v80
	v_lshlrev_b32_e32 v25, 16, v81
	v_and_b32_e32 v81, 0xffff0000, v81
	v_lshlrev_b32_e32 v26, 16, v82
	v_and_b32_e32 v82, 0xffff0000, v82
	v_lshlrev_b32_e32 v27, 16, v83
	v_and_b32_e32 v83, 0xffff0000, v83
	v_mul_f32_e32 v24, v20, v24
	v_mul_f32_e32 v80, v20, v80
	v_mul_f32_e32 v25, v20, v25
	v_mul_f32_e32 v81, v20, v81
	v_mul_f32_e32 v26, v20, v26
	v_mul_f32_e32 v82, v20, v82
	v_mul_f32_e32 v27, v20, v27
	v_mul_f32_e32 v83, v20, v83
	v_cvt_pk_bf16_f32 v80, v24, v80
	v_cvt_pk_bf16_f32 v81, v25, v81
	v_cvt_pk_bf16_f32 v82, v26, v82
	v_cvt_pk_bf16_f32 v83, v27, v83
	ds_write_b128 v2, v[80:83] offset:16384
	s_waitcnt vmcnt(10)
	v_lshlrev_b32_e32 v24, 16, v84
	v_and_b32_e32 v84, 0xffff0000, v84
	v_lshlrev_b32_e32 v25, 16, v85
	v_and_b32_e32 v85, 0xffff0000, v85
	v_lshlrev_b32_e32 v26, 16, v86
	v_and_b32_e32 v86, 0xffff0000, v86
	v_lshlrev_b32_e32 v27, 16, v87
	v_and_b32_e32 v87, 0xffff0000, v87
	v_mul_f32_e32 v24, v21, v24
	v_mul_f32_e32 v84, v21, v84
	v_mul_f32_e32 v25, v21, v25
	v_mul_f32_e32 v85, v21, v85
	v_mul_f32_e32 v26, v21, v26
	v_mul_f32_e32 v86, v21, v86
	v_mul_f32_e32 v27, v21, v27
	v_mul_f32_e32 v87, v21, v87
	v_cvt_pk_bf16_f32 v84, v24, v84
	v_cvt_pk_bf16_f32 v85, v25, v85
	v_cvt_pk_bf16_f32 v86, v26, v86
	v_cvt_pk_bf16_f32 v87, v27, v87
	ds_write_b128 v2, v[84:87] offset:20480
	s_waitcnt vmcnt(9)
	v_lshlrev_b32_e32 v24, 16, v88
	v_and_b32_e32 v88, 0xffff0000, v88
	v_lshlrev_b32_e32 v25, 16, v89
	v_and_b32_e32 v89, 0xffff0000, v89
	v_lshlrev_b32_e32 v26, 16, v90
	v_and_b32_e32 v90, 0xffff0000, v90
	v_lshlrev_b32_e32 v27, 16, v91
	v_and_b32_e32 v91, 0xffff0000, v91
	v_mul_f32_e32 v24, v22, v24
	v_mul_f32_e32 v88, v22, v88
	v_mul_f32_e32 v25, v22, v25
	v_mul_f32_e32 v89, v22, v89
	v_mul_f32_e32 v26, v22, v26
	v_mul_f32_e32 v90, v22, v90
	v_mul_f32_e32 v27, v22, v27
	v_mul_f32_e32 v91, v22, v91
	v_cvt_pk_bf16_f32 v88, v24, v88
	v_cvt_pk_bf16_f32 v89, v25, v89
	v_cvt_pk_bf16_f32 v90, v26, v90
	v_cvt_pk_bf16_f32 v91, v27, v91
	ds_write_b128 v2, v[88:91] offset:24576
	s_waitcnt vmcnt(8)
	v_lshlrev_b32_e32 v24, 16, v92
	v_and_b32_e32 v92, 0xffff0000, v92
	v_lshlrev_b32_e32 v25, 16, v93
	v_and_b32_e32 v93, 0xffff0000, v93
	v_lshlrev_b32_e32 v26, 16, v94
	v_and_b32_e32 v94, 0xffff0000, v94
	v_lshlrev_b32_e32 v27, 16, v95
	v_and_b32_e32 v95, 0xffff0000, v95
	v_mul_f32_e32 v24, v23, v24
	v_mul_f32_e32 v92, v23, v92
	v_mul_f32_e32 v25, v23, v25
	v_mul_f32_e32 v93, v23, v93
	v_mul_f32_e32 v26, v23, v26
	v_mul_f32_e32 v94, v23, v94
	v_mul_f32_e32 v27, v23, v27
	v_mul_f32_e32 v95, v23, v95
	v_cvt_pk_bf16_f32 v92, v24, v92
	v_cvt_pk_bf16_f32 v93, v25, v93
	v_cvt_pk_bf16_f32 v94, v26, v94
	v_cvt_pk_bf16_f32 v95, v27, v95
	ds_write_b128 v2, v[92:95] offset:28672
	s_waitcnt vmcnt(7)
	ds_write_b128 v5, v[96:99] offset:0
	s_waitcnt vmcnt(6)
	ds_write_b128 v5, v[100:103] offset:4096
	s_waitcnt vmcnt(5)
	ds_write_b128 v5, v[104:107] offset:8192
	s_waitcnt vmcnt(4)
	ds_write_b128 v5, v[108:111] offset:12288
	s_waitcnt vmcnt(3)
	ds_write_b128 v5, v[112:115] offset:16384
	s_waitcnt vmcnt(2)
	ds_write_b128 v5, v[116:119] offset:20480
	s_waitcnt vmcnt(1)
	ds_write_b128 v5, v[120:123] offset:24576
	s_waitcnt vmcnt(0)
	ds_write_b128 v5, v[124:127] offset:28672
	s_branch .Lkv_join
.Lkv_small:
	global_load_dwordx4 v[64:67], v3, s[6:7]
	global_load_dwordx4 v[96:99], v3, s[8:9]
	v_mov_b32_e32 v68, 0
	v_mov_b32_e32 v69, 0
	v_mov_b32_e32 v70, 0
	v_mov_b32_e32 v71, 0
	v_mov_b32_e32 v7, v6
	v_cvt_f32_i32_e32 v7, v7
	v_mul_f32_e32 v7, v12, v7
	v_exp_f32_e32 v16, v7
	ds_write_b128 v2, v[68:71] offset:4096
	ds_write_b128 v5, v[68:71] offset:4096
	ds_write_b128 v2, v[68:71] offset:8192
	ds_write_b128 v5, v[68:71] offset:8192
	ds_write_b128 v2, v[68:71] offset:12288
	ds_write_b128 v5, v[68:71] offset:12288
	ds_write_b128 v2, v[68:71] offset:16384
	ds_write_b128 v5, v[68:71] offset:16384
	ds_write_b128 v2, v[68:71] offset:20480
	ds_write_b128 v5, v[68:71] offset:20480
	ds_write_b128 v2, v[68:71] offset:24576
	ds_write_b128 v5, v[68:71] offset:24576
	ds_write_b128 v2, v[68:71] offset:28672
	ds_write_b128 v5, v[68:71] offset:28672
	s_waitcnt vmcnt(1)
	v_lshlrev_b32_e32 v24, 16, v64
	v_and_b32_e32 v64, 0xffff0000, v64
	v_lshlrev_b32_e32 v25, 16, v65
	v_and_b32_e32 v65, 0xffff0000, v65
	v_lshlrev_b32_e32 v26, 16, v66
	v_and_b32_e32 v66, 0xffff0000, v66
	v_lshlrev_b32_e32 v27, 16, v67
	v_and_b32_e32 v67, 0xffff0000, v67
	v_mul_f32_e32 v24, v16, v24
	v_mul_f32_e32 v64, v16, v64
	v_mul_f32_e32 v25, v16, v25
	v_mul_f32_e32 v65, v16, v65
	v_mul_f32_e32 v26, v16, v26
	v_mul_f32_e32 v66, v16, v66
	v_mul_f32_e32 v27, v16, v27
	v_mul_f32_e32 v67, v16, v67
	v_cvt_pk_bf16_f32 v64, v24, v64
	v_cvt_pk_bf16_f32 v65, v25, v65
	v_cvt_pk_bf16_f32 v66, v26, v66
	v_cvt_pk_bf16_f32 v67, v27, v67
	ds_write_b128 v2, v[64:67] offset:0
	s_waitcnt vmcnt(0)
	ds_write_b128 v5, v[96:99]
.Lkv_join:
	s_mul_i32 s6, s41, 17
	s_add_i32 s90, s6, s40
	s_ashr_i32 s13, s39, 1
	s_lshl_b32 s6, s39, 1
	s_and_b32 s8, s13, 0xffffffc0
	s_and_b32 s9, s6, 0x80
	s_lshl_b64 s[6:7], s[90:91], 18
	v_readlane_b32 s41, v254, 38
	s_add_u32 s6, s41, s6
	v_readlane_b32 s40, v254, 39
	s_addc_u32 s7, s40, s7
	s_and_b32 s10, s13, 0xffff80
	s_lshl_b32 s12, s39, 9
	s_lshl_b32 s13, s13, 8
	s_max_u32 s11, s33, 32
	s_and_b32 s12, s12, 0x8000
	s_and_b32 s13, s13, 0xffff8000
	s_lshl_b32 s11, s11, 8
	s_add_i32 s12, s12, 0
	s_add_i32 s13, s13, 0
	s_and_b32 s11, s11, 0xe000
	s_add_i32 s12, s12, 0x10400
	s_addk_i32 s13, 0x400
	s_mov_b32 s14, 0
	s_add_i32 s28, 0, 0x10000
	s_waitcnt lgkmcnt(0)
	s_barrier

; #define G_STAGE(bufoff, gbase, voff) do { _Pragma("unroll") for (int _i = 0; _i < 2; ++_i) \
;         __builtin_amdgcn_global_load_lds((const unsigned*)((const char*)(gbase) + (voff)[_i]), (LAS unsigned*)(lds + (bufoff) + ldsw + _i * 8192), 16, 0, 0); } while (0)
; #define G_LDA(dst, b, h) do { _Pragma("unroll") for (int m = 0; m < 4; ++m) _Pragma("unroll") for (int k = 0; k < 2; ++k) dst[m][k] = *(const LAS bf16x8*)(lds + G_SA(b, h) + aoff + m * 2048 + k * 1024); } while (0)
; #define G_LDB(dst, b, h) do { _Pragma("unroll") for (int n = 0; n < 2; ++n) _Pragma("unroll") for (int k = 0; k < 2; ++k) dst[n][k] = *(const LAS bf16x8*)(lds + G_SB(b, h) + boff + n * 2048 + k * 1024); } while (0)
; #define G_MMA(ai, bj, At, Bt) do { __builtin_amdgcn_s_setprio(1); _Pragma("unroll") for (int m = 0; m < 4; ++m) _Pragma("unroll") for (int n = 0; n < 2; ++n) _Pragma("unroll") for (int k = 0; k < 2; ++k) \
;         acc[ai][bj][m][n] = __builtin_amdgcn_mfma_f32_16x16x32_bf16(Bt[n][k], At[m][k], acc[ai][bj][m][n], 0, 0, 0); __builtin_amdgcn_s_setprio(0); } while (0)
; #define G_WAIT_V(n) asm volatile("s_waitcnt vmcnt(" #n ")" ::: "memory")
; #define G_WAIT_L(n) asm volatile("s_waitcnt lgkmcnt(" #n ")" ::: "memory")
; #define G_BAR __builtin_amdgcn_s_barrier()
; #define G_SCHED __builtin_amdgcn_sched_barrier(0)
; template <class Epi, class Sched>
; __device__ __forceinline__ void gemm_phase(LAS unsigned char* lds, const Sched& S, const Epi& E, const int K, const int lda, const int ldb, const int tid) {
;     ...
;             G_LDB(B0, 0, 0); G_SCHED; G_LDA(At, 0, 0); G_STAGE(G_SA(1, 1), a1 + hstepA, voffA);
;             G_WAIT_L(8); G_BAR; G_WAIT_L(0); G_MMA(0, 0, At, B0); G_BAR; G_SCHED;
;             G_LDB(B1, 0, 1); G_STAGE(G_SB(0, 0), b2, voffB);
;             G_BAR; G_WAIT_L(0); G_MMA(0, 1, At, B1); G_BAR;
;             G_LDA(At, 0, 1); G_STAGE(G_SA(0, 0), a2, voffA);
;             G_BAR; G_WAIT_L(0); G_MMA(1, 0, At, B0); G_BAR; G_SCHED;
;             G_STAGE(G_SB(0, 1), b2 + hstepB, voffB);
;             G_WAIT_V(6); G_BAR; G_MMA(1, 1, At, B1); G_BAR;
.LBB0_556:
	s_add_u32 s20, s18, 0xfff80080
	s_addc_u32 s21, s19, -1
	s_add_i32 s43, 0, 0x10000
	v_add_u32_e32 v0, s43, v197
	ds_read_b128 v[130:133], v0
	ds_read_b128 v[134:137], v0 offset:1024
	ds_read_b128 v[138:141], v0 offset:2048
	ds_read_b128 v[142:145], v0 offset:3072
	s_cmp_eq_u32 s41, 28
	s_cselect_b32 s23, s1, s21
	s_cselect_b32 s22, s11, s20
	s_cselect_b32 s21, s13, s40
	s_cselect_b32 s20, s33, s39
	v_lshl_add_u64 v[192:193], s[18:19], 0, v[158:159]
	s_add_i32 m0, s29, 0xc000
	ds_read_b128 v[162:165], v201
	ds_read_b128 v[166:169], v201 offset:1024
	ds_read_b128 v[170:173], v201 offset:2048
	ds_read_b128 v[174:177], v201 offset:3072
	ds_read_b128 v[178:181], v201 offset:4096
	ds_read_b128 v[182:185], v201 offset:5120
	ds_read_b128 v[186:189], v201 offset:6144
	ds_read_b128 v[202:205], v201 offset:7168
	global_load_lds_dwordx4 v[192:193], off
	v_lshl_add_u64 v[192:193], s[18:19], 0, v[160:161]
	s_add_i32 m0, s29, 0xe000
	s_nop 0
	global_load_lds_dwordx4 v[192:193], off
	s_waitcnt lgkmcnt(8)
	s_barrier
	s_waitcnt lgkmcnt(0)
	s_setprio 1
	s_waitcnt lgkmcnt(0)
	v_mfma_f32_16x16x32_bf16 v[126:129], v[130:133], v[162:165], v[126:129]
	v_mfma_f32_16x16x32_bf16 v[122:125], v[138:141], v[162:165], v[122:125]
	v_mfma_f32_16x16x32_bf16 v[110:113], v[130:133], v[170:173], v[110:113]
	v_mfma_f32_16x16x32_bf16 v[106:109], v[138:141], v[170:173], v[106:109]
	v_mfma_f32_16x16x32_bf16 v[94:97], v[130:133], v[178:181], v[94:97]
	v_mfma_f32_16x16x32_bf16 v[90:93], v[138:141], v[178:181], v[90:93]
	v_mfma_f32_16x16x32_bf16 v[78:81], v[130:133], v[186:189], v[78:81]
	v_mfma_f32_16x16x32_bf16 v[74:77], v[138:141], v[186:189], v[74:77]
	v_mfma_f32_16x16x32_bf16 v[126:129], v[134:137], v[166:169], v[126:129]
	v_mfma_f32_16x16x32_bf16 v[122:125], v[142:145], v[166:169], v[122:125]
	v_mfma_f32_16x16x32_bf16 v[110:113], v[134:137], v[174:177], v[110:113]
	v_mfma_f32_16x16x32_bf16 v[106:109], v[142:145], v[174:177], v[106:109]
	v_mfma_f32_16x16x32_bf16 v[94:97], v[134:137], v[182:185], v[94:97]
	v_mfma_f32_16x16x32_bf16 v[90:93], v[142:145], v[182:185], v[90:93]
	v_mfma_f32_16x16x32_bf16 v[78:81], v[134:137], v[202:205], v[78:81]
	v_mfma_f32_16x16x32_bf16 v[74:77], v[142:145], v[202:205], v[74:77]
	s_setprio 0
	s_barrier
	s_add_i32 s62, 0, 0x14000
	s_add_i32 s43, s43, s27
	v_add_u32_e32 v0, s62, v197
	v_lshl_add_u64 v[192:193], s[20:21], 0, v[150:151]
	s_mov_b32 m0, s43
	ds_read_b128 v[206:209], v0
	ds_read_b128 v[210:213], v0 offset:1024
	ds_read_b128 v[214:217], v0 offset:2048
	ds_read_b128 v[218:221], v0 offset:3072
	global_load_lds_dwordx4 v[192:193], off
	v_lshl_add_u64 v[194:195], s[20:21], 0, v[146:147]
	s_add_i32 m0, s43, 0x2000
	s_nop 0
	global_load_lds_dwordx4 v[194:195], off
	s_barrier
	s_waitcnt lgkmcnt(0)
	s_setprio 1
	s_waitcnt lgkmcnt(0)
	v_mfma_f32_16x16x32_bf16 v[118:121], v[206:209], v[162:165], v[118:121]
	v_mfma_f32_16x16x32_bf16 v[114:117], v[214:217], v[162:165], v[114:117]
	v_mfma_f32_16x16x32_bf16 v[102:105], v[206:209], v[170:173], v[102:105]
	v_mfma_f32_16x16x32_bf16 v[98:101], v[214:217], v[170:173], v[98:101]
	v_mfma_f32_16x16x32_bf16 v[86:89], v[206:209], v[178:181], v[86:89]
	v_mfma_f32_16x16x32_bf16 v[82:85], v[214:217], v[178:181], v[82:85]
	v_mfma_f32_16x16x32_bf16 v[70:73], v[206:209], v[186:189], v[70:73]
	v_mfma_f32_16x16x32_bf16 v[66:69], v[214:217], v[186:189], v[66:69]
	v_mfma_f32_16x16x32_bf16 v[118:121], v[210:213], v[166:169], v[118:121]
	v_mfma_f32_16x16x32_bf16 v[114:117], v[218:221], v[166:169], v[114:117]
	v_mfma_f32_16x16x32_bf16 v[102:105], v[210:213], v[174:177], v[102:105]
	v_mfma_f32_16x16x32_bf16 v[98:101], v[218:221], v[174:177], v[98:101]
	v_mfma_f32_16x16x32_bf16 v[86:89], v[210:213], v[182:185], v[86:89]
	v_mfma_f32_16x16x32_bf16 v[82:85], v[218:221], v[182:185], v[82:85]
	v_mfma_f32_16x16x32_bf16 v[70:73], v[210:213], v[202:205], v[70:73]
	v_mfma_f32_16x16x32_bf16 v[66:69], v[218:221], v[202:205], v[66:69]
	s_setprio 0
	s_mov_b32 m0, s29
	v_lshl_add_u64 v[198:199], s[22:23], 0, v[152:153]
	s_barrier
	ds_read_b128 v[162:165], v201 offset:16384
	ds_read_b128 v[166:169], v201 offset:17408
	ds_read_b128 v[170:173], v201 offset:18432
	ds_read_b128 v[174:177], v201 offset:19456
	ds_read_b128 v[178:181], v201 offset:20480
	ds_read_b128 v[182:185], v201 offset:21504
	ds_read_b128 v[186:189], v201 offset:22528
	ds_read_b128 v[202:205], v201 offset:23552
	global_load_lds_dwordx4 v[198:199], off
	v_lshl_add_u64 v[222:223], s[22:23], 0, v[148:149]
	s_mov_b32 m0, s30
	s_nop 0
	global_load_lds_dwordx4 v[222:223], off
	s_barrier
	s_waitcnt lgkmcnt(0)
	s_setprio 1
	s_waitcnt lgkmcnt(0)
	v_mfma_f32_16x16x32_bf16 v[62:65], v[130:133], v[162:165], v[62:65]
	v_mfma_f32_16x16x32_bf16 v[58:61], v[138:141], v[162:165], v[58:61]
	v_mfma_f32_16x16x32_bf16 v[46:49], v[130:133], v[170:173], v[46:49]
	v_mfma_f32_16x16x32_bf16 v[42:45], v[138:141], v[170:173], v[42:45]
	v_mfma_f32_16x16x32_bf16 v[30:33], v[130:133], v[178:181], v[30:33]
	v_mfma_f32_16x16x32_bf16 v[26:29], v[138:141], v[178:181], v[26:29]
	v_mfma_f32_16x16x32_bf16 v[14:17], v[130:133], v[186:189], v[14:17]
	v_mfma_f32_16x16x32_bf16 v[10:13], v[138:141], v[186:189], v[10:13]
	v_mfma_f32_16x16x32_bf16 v[62:65], v[134:137], v[166:169], v[62:65]
	v_mfma_f32_16x16x32_bf16 v[58:61], v[142:145], v[166:169], v[58:61]
	v_mfma_f32_16x16x32_bf16 v[46:49], v[134:137], v[174:177], v[46:49]
	v_mfma_f32_16x16x32_bf16 v[42:45], v[142:145], v[174:177], v[42:45]
	v_mfma_f32_16x16x32_bf16 v[30:33], v[134:137], v[182:185], v[30:33]
	v_mfma_f32_16x16x32_bf16 v[26:29], v[142:145], v[182:185], v[26:29]
	v_mfma_f32_16x16x32_bf16 v[14:17], v[134:137], v[202:205], v[14:17]
	v_mfma_f32_16x16x32_bf16 v[10:13], v[142:145], v[202:205], v[10:13]
	s_setprio 0
	s_barrier
; #define G_STAGE(bufoff, gbase, voff) do { _Pragma("unroll") for (int _i = 0; _i < 2; ++_i) \
;         __builtin_amdgcn_global_load_lds((const unsigned*)((const char*)(gbase) + (voff)[_i]), (LAS unsigned*)(lds + (bufoff) + ldsw + _i * 8192), 16, 0, 0); } while (0)
; #define G_LDA(dst, b, h) do { _Pragma("unroll") for (int m = 0; m < 4; ++m) _Pragma("unroll") for (int k = 0; k < 2; ++k) dst[m][k] = *(const LAS bf16x8*)(lds + G_SA(b, h) + aoff + m * 2048 + k * 1024); } while (0)
; #define G_LDB(dst, b, h) do { _Pragma("unroll") for (int n = 0; n < 2; ++n) _Pragma("unroll") for (int k = 0; k < 2; ++k) dst[n][k] = *(const LAS bf16x8*)(lds + G_SB(b, h) + boff + n * 2048 + k * 1024); } while (0)
; #define G_MMA(ai, bj, At, Bt) do { __builtin_amdgcn_s_setprio(1); _Pragma("unroll") for (int m = 0; m < 4; ++m) _Pragma("unroll") for (int n = 0; n < 2; ++n) _Pragma("unroll") for (int k = 0; k < 2; ++k) \
;         acc[ai][bj][m][n] = __builtin_amdgcn_mfma_f32_16x16x32_bf16(Bt[n][k], At[m][k], acc[ai][bj][m][n], 0, 0, 0); __builtin_amdgcn_s_setprio(0); } while (0)
; #define G_WAIT_V(n) asm volatile("s_waitcnt vmcnt(" #n ")" ::: "memory")
; #define G_WAIT_L(n) asm volatile("s_waitcnt lgkmcnt(" #n ")" ::: "memory")
; #define G_BAR __builtin_amdgcn_s_barrier()
; #define G_SCHED __builtin_amdgcn_sched_barrier(0)
; template <class Epi, class Sched>
; __device__ __forceinline__ void gemm_phase(LAS unsigned char* lds, const Sched& S, const Epi& E, const int K, const int lda, const int ldb, const int tid) {
;     ...
;             G_STAGE(G_SB(0, 1), b2 + hstepB, voffB);
;             G_WAIT_V(6); G_BAR; G_MMA(1, 1, At, B1); G_BAR;
;             G_LDB(B0, 1, 0); G_SCHED; G_LDA(At, 1, 0); G_STAGE(G_SA(0, 1), a2 + hstepA, voffA);
;             G_WAIT_L(8); G_BAR; G_WAIT_L(0); G_MMA(0, 0, At, B0); G_BAR; G_SCHED;
;             G_LDB(B1, 1, 1); G_STAGE(G_SB(1, 0), b3, voffB);
;             G_BAR; G_WAIT_L(0); G_MMA(0, 1, At, B1); G_BAR;
;             G_LDA(At, 1, 1); G_STAGE(G_SA(1, 0), a3, voffA);
;             G_BAR; G_WAIT_L(0); G_MMA(1, 0, At, B0); G_BAR; G_SCHED;
	s_add_u32 s60, s20, 0x80000
	s_addc_u32 s61, s21, 0
	s_add_i32 s43, s62, s27
	v_lshl_add_u64 v[130:131], s[60:61], 0, v[150:151]
	s_mov_b32 m0, s43
	s_nop 0
	global_load_lds_dwordx4 v[130:131], off
	v_lshl_add_u64 v[130:131], s[60:61], 0, v[146:147]
	s_add_i32 m0, s43, 0x2000
	s_nop 0
	global_load_lds_dwordx4 v[130:131], off
	s_waitcnt vmcnt(6)
	s_barrier
	s_setprio 1
	v_mfma_f32_16x16x32_bf16 v[54:57], v[206:209], v[162:165], v[54:57]
	v_mfma_f32_16x16x32_bf16 v[50:53], v[214:217], v[162:165], v[50:53]
	v_mfma_f32_16x16x32_bf16 v[38:41], v[206:209], v[170:173], v[38:41]
	v_mfma_f32_16x16x32_bf16 v[34:37], v[214:217], v[170:173], v[34:37]
	v_mfma_f32_16x16x32_bf16 v[22:25], v[206:209], v[178:181], v[22:25]
	v_mfma_f32_16x16x32_bf16 v[18:21], v[214:217], v[178:181], v[18:21]
	v_mfma_f32_16x16x32_bf16 v[6:9], v[206:209], v[186:189], v[6:9]
	v_mfma_f32_16x16x32_bf16 v[2:5], v[214:217], v[186:189], v[2:5]
	v_mfma_f32_16x16x32_bf16 v[54:57], v[210:213], v[166:169], v[54:57]
	v_mfma_f32_16x16x32_bf16 v[50:53], v[218:221], v[166:169], v[50:53]
	v_mfma_f32_16x16x32_bf16 v[38:41], v[210:213], v[174:177], v[38:41]
	v_mfma_f32_16x16x32_bf16 v[34:37], v[218:221], v[174:177], v[34:37]
	v_mfma_f32_16x16x32_bf16 v[22:25], v[210:213], v[182:185], v[22:25]
	v_mfma_f32_16x16x32_bf16 v[18:21], v[218:221], v[182:185], v[18:21]
	v_mfma_f32_16x16x32_bf16 v[6:9], v[210:213], v[202:205], v[6:9]
	v_mfma_f32_16x16x32_bf16 v[2:5], v[218:221], v[202:205], v[2:5]
	s_setprio 0
	s_add_i32 s43, 0, 0x18000
	v_add_u32_e32 v0, s43, v197
	s_barrier
	ds_read_b128 v[130:133], v0
	ds_read_b128 v[134:137], v0 offset:1024
	ds_read_b128 v[138:141], v0 offset:2048
	ds_read_b128 v[142:145], v0 offset:3072
	s_add_u32 s22, s22, 0x80000
	s_addc_u32 s23, s23, 0
	s_mov_b32 m0, s31
	v_lshl_add_u64 v[206:207], s[22:23], 0, v[152:153]
	ds_read_b128 v[162:165], v201 offset:32768
	ds_read_b128 v[166:169], v201 offset:33792
	ds_read_b128 v[170:173], v201 offset:34816
	ds_read_b128 v[174:177], v201 offset:35840
	ds_read_b128 v[178:181], v201 offset:36864
	ds_read_b128 v[182:185], v201 offset:37888
	ds_read_b128 v[186:189], v201 offset:38912
	ds_read_b128 v[202:205], v201 offset:39936
	global_load_lds_dwordx4 v[206:207], off
	v_lshl_add_u64 v[206:207], s[22:23], 0, v[148:149]
	s_mov_b32 m0, s34
	s_nop 0
	global_load_lds_dwordx4 v[206:207], off
	s_waitcnt lgkmcnt(8)
	s_barrier
	s_waitcnt lgkmcnt(0)
	s_setprio 1
	s_waitcnt lgkmcnt(0)
	v_mfma_f32_16x16x32_bf16 v[126:129], v[130:133], v[162:165], v[126:129]
	v_mfma_f32_16x16x32_bf16 v[122:125], v[138:141], v[162:165], v[122:125]
	v_mfma_f32_16x16x32_bf16 v[110:113], v[130:133], v[170:173], v[110:113]
	v_mfma_f32_16x16x32_bf16 v[106:109], v[138:141], v[170:173], v[106:109]
	v_mfma_f32_16x16x32_bf16 v[94:97], v[130:133], v[178:181], v[94:97]
	v_mfma_f32_16x16x32_bf16 v[90:93], v[138:141], v[178:181], v[90:93]
	v_mfma_f32_16x16x32_bf16 v[78:81], v[130:133], v[186:189], v[78:81]
	v_mfma_f32_16x16x32_bf16 v[74:77], v[138:141], v[186:189], v[74:77]
	v_mfma_f32_16x16x32_bf16 v[126:129], v[134:137], v[166:169], v[126:129]
	v_mfma_f32_16x16x32_bf16 v[122:125], v[142:145], v[166:169], v[122:125]
	v_mfma_f32_16x16x32_bf16 v[110:113], v[134:137], v[174:177], v[110:113]
	v_mfma_f32_16x16x32_bf16 v[106:109], v[142:145], v[174:177], v[106:109]
	v_mfma_f32_16x16x32_bf16 v[94:97], v[134:137], v[182:185], v[94:97]
	v_mfma_f32_16x16x32_bf16 v[90:93], v[142:145], v[182:185], v[90:93]
	v_mfma_f32_16x16x32_bf16 v[78:81], v[134:137], v[202:205], v[78:81]
	v_mfma_f32_16x16x32_bf16 v[74:77], v[142:145], v[202:205], v[74:77]
	s_setprio 0
	s_barrier
	s_add_i32 s22, 0, 0x1c000
	s_add_i32 s23, s43, s27
	v_add_u32_e32 v0, s22, v197
	v_lshl_add_u64 v[192:193], v[192:193], 0, s[92:93]
	s_mov_b32 m0, s23
	ds_read_b128 v[206:209], v0
	ds_read_b128 v[210:213], v0 offset:1024
	ds_read_b128 v[214:217], v0 offset:2048
	ds_read_b128 v[218:221], v0 offset:3072
	global_load_lds_dwordx4 v[192:193], off
	v_lshl_add_u64 v[192:193], v[194:195], 0, s[92:93]
	s_add_i32 m0, s23, 0x2000
	s_nop 0
	global_load_lds_dwordx4 v[192:193], off
	s_barrier
	s_waitcnt lgkmcnt(0)
	s_setprio 1
	s_waitcnt lgkmcnt(0)
	v_mfma_f32_16x16x32_bf16 v[118:121], v[206:209], v[162:165], v[118:121]
	v_mfma_f32_16x16x32_bf16 v[114:117], v[214:217], v[162:165], v[114:117]
	v_mfma_f32_16x16x32_bf16 v[102:105], v[206:209], v[170:173], v[102:105]
	v_mfma_f32_16x16x32_bf16 v[98:101], v[214:217], v[170:173], v[98:101]
	v_mfma_f32_16x16x32_bf16 v[86:89], v[206:209], v[178:181], v[86:89]
	v_mfma_f32_16x16x32_bf16 v[82:85], v[214:217], v[178:181], v[82:85]
	v_mfma_f32_16x16x32_bf16 v[70:73], v[206:209], v[186:189], v[70:73]
	v_mfma_f32_16x16x32_bf16 v[66:69], v[214:217], v[186:189], v[66:69]
	v_mfma_f32_16x16x32_bf16 v[118:121], v[210:213], v[166:169], v[118:121]
	v_mfma_f32_16x16x32_bf16 v[114:117], v[218:221], v[166:169], v[114:117]
	v_mfma_f32_16x16x32_bf16 v[102:105], v[210:213], v[174:177], v[102:105]
	v_mfma_f32_16x16x32_bf16 v[98:101], v[218:221], v[174:177], v[98:101]
	v_mfma_f32_16x16x32_bf16 v[86:89], v[210:213], v[182:185], v[86:89]
	v_mfma_f32_16x16x32_bf16 v[82:85], v[218:221], v[182:185], v[82:85]
	v_mfma_f32_16x16x32_bf16 v[70:73], v[210:213], v[202:205], v[70:73]
	v_mfma_f32_16x16x32_bf16 v[66:69], v[218:221], v[202:205], v[66:69]
	s_setprio 0
	s_mov_b32 m0, s35
	v_lshl_add_u64 v[192:193], v[198:199], 0, s[92:93]
	s_barrier
	ds_read_b128 v[162:165], v201 offset:49152
	ds_read_b128 v[166:169], v201 offset:50176
	ds_read_b128 v[170:173], v201 offset:51200
	ds_read_b128 v[174:177], v201 offset:52224
	ds_read_b128 v[178:181], v201 offset:53248
	ds_read_b128 v[182:185], v201 offset:54272
	ds_read_b128 v[186:189], v201 offset:55296
	ds_read_b128 v[202:205], v201 offset:56320
	global_load_lds_dwordx4 v[192:193], off
	v_lshl_add_u64 v[192:193], v[222:223], 0, s[92:93]
	s_mov_b32 m0, s36
	s_nop 0
	global_load_lds_dwordx4 v[192:193], off
	s_barrier
; #define G_STAGE(bufoff, gbase, voff) do { _Pragma("unroll") for (int _i = 0; _i < 2; ++_i) \
;         __builtin_amdgcn_global_load_lds((const unsigned*)((const char*)(gbase) + (voff)[_i]), (LAS unsigned*)(lds + (bufoff) + ldsw + _i * 8192), 16, 0, 0); } while (0)
; #define G_MMA(ai, bj, At, Bt) do { __builtin_amdgcn_s_setprio(1); _Pragma("unroll") for (int m = 0; m < 4; ++m) _Pragma("unroll") for (int n = 0; n < 2; ++n) _Pragma("unroll") for (int k = 0; k < 2; ++k) \
;         acc[ai][bj][m][n] = __builtin_amdgcn_mfma_f32_16x16x32_bf16(Bt[n][k], At[m][k], acc[ai][bj][m][n], 0, 0, 0); __builtin_amdgcn_s_setprio(0); } while (0)
; #define G_WAIT_V(n) asm volatile("s_waitcnt vmcnt(" #n ")" ::: "memory")
; #define G_WAIT_L(n) asm volatile("s_waitcnt lgkmcnt(" #n ")" ::: "memory")
; #define G_BAR __builtin_amdgcn_s_barrier()
; #define G_SCHED __builtin_amdgcn_sched_barrier(0)
; template <class Epi, class Sched>
; __device__ __forceinline__ void gemm_phase(LAS unsigned char* lds, const Sched& S, const Epi& E, const int K, const int lda, const int ldb, const int tid) {
;     ...
;             G_BAR; G_WAIT_L(0); G_MMA(1, 0, At, B0); G_BAR; G_SCHED;
;             G_STAGE(G_SB(1, 1), b3 + hstepB, voffB);
;             G_WAIT_V(6); G_BAR; G_MMA(1, 1, At, B1); G_BAR;
;         }
;         const bool keep = E(acc, cur, wr, wc, fr, fq);
;     template <int KIND>
;     __device__ __forceinline__ void body(f32x4 (&acc)[2][2][4][2], const Unit& un, int wr, int wc, int fr, int fq) const {
;     ...
;         float rstd[8];
; #pragma unroll
;         for (int i = 0; i < 8; ++i) rstd[i] = rsq[rbase + (i >> 2) * 128 + (i & 3) * 16];
;         f32x4 cfv[4];
;         if (KIND == 2 || KIND == 3) {
; #pragma unroll
;             for (int t = 0; t < 4; ++t) cfv[t] = *(const f32x4*)(cf + (size_t)cw * 2 + t * 4);
;         }
; #pragma unroll
;         for (int i = 0; i < 8; ++i) rstd[i] = rsqrtf(rstd[i] * (1.0f / 2048.0f) + EPS);
	s_waitcnt lgkmcnt(0)
	s_setprio 1
	s_waitcnt lgkmcnt(0)
	v_mfma_f32_16x16x32_bf16 v[62:65], v[130:133], v[162:165], v[62:65]
	v_mfma_f32_16x16x32_bf16 v[58:61], v[138:141], v[162:165], v[58:61]
	v_mfma_f32_16x16x32_bf16 v[46:49], v[130:133], v[170:173], v[46:49]
	v_mfma_f32_16x16x32_bf16 v[42:45], v[138:141], v[170:173], v[42:45]
	v_mfma_f32_16x16x32_bf16 v[30:33], v[130:133], v[178:181], v[30:33]
	v_mfma_f32_16x16x32_bf16 v[26:29], v[138:141], v[178:181], v[26:29]
	v_mfma_f32_16x16x32_bf16 v[14:17], v[130:133], v[186:189], v[14:17]
	v_mfma_f32_16x16x32_bf16 v[10:13], v[138:141], v[186:189], v[10:13]
	v_mfma_f32_16x16x32_bf16 v[62:65], v[134:137], v[166:169], v[62:65]
	v_mfma_f32_16x16x32_bf16 v[58:61], v[142:145], v[166:169], v[58:61]
	v_mfma_f32_16x16x32_bf16 v[46:49], v[134:137], v[174:177], v[46:49]
	v_mfma_f32_16x16x32_bf16 v[42:45], v[142:145], v[174:177], v[42:45]
	v_mfma_f32_16x16x32_bf16 v[30:33], v[134:137], v[182:185], v[30:33]
	v_mfma_f32_16x16x32_bf16 v[26:29], v[142:145], v[182:185], v[26:29]
	v_mfma_f32_16x16x32_bf16 v[14:17], v[134:137], v[202:205], v[14:17]
	v_mfma_f32_16x16x32_bf16 v[10:13], v[142:145], v[202:205], v[10:13]
	s_setprio 0
	s_barrier
	s_add_u32 s20, s20, 0x80080
	s_addc_u32 s21, s21, 0
	s_add_i32 s22, s22, s27
	v_lshl_add_u64 v[130:131], s[20:21], 0, v[150:151]
	s_mov_b32 m0, s22
	s_nop 0
	global_load_lds_dwordx4 v[130:131], off
	v_lshl_add_u64 v[130:131], s[20:21], 0, v[146:147]
	s_add_i32 m0, s22, 0x2000
	s_nop 0
	global_load_lds_dwordx4 v[130:131], off
	s_waitcnt vmcnt(6)
	s_barrier
	s_setprio 1
	v_mfma_f32_16x16x32_bf16 v[54:57], v[206:209], v[162:165], v[54:57]
	v_mfma_f32_16x16x32_bf16 v[50:53], v[214:217], v[162:165], v[50:53]
	v_mfma_f32_16x16x32_bf16 v[38:41], v[206:209], v[170:173], v[38:41]
	v_mfma_f32_16x16x32_bf16 v[34:37], v[214:217], v[170:173], v[34:37]
	v_mfma_f32_16x16x32_bf16 v[22:25], v[206:209], v[178:181], v[22:25]
	v_mfma_f32_16x16x32_bf16 v[18:21], v[214:217], v[178:181], v[18:21]
	v_mfma_f32_16x16x32_bf16 v[6:9], v[206:209], v[186:189], v[6:9]
	v_mfma_f32_16x16x32_bf16 v[2:5], v[214:217], v[186:189], v[2:5]
	v_mfma_f32_16x16x32_bf16 v[54:57], v[210:213], v[166:169], v[54:57]
	v_mfma_f32_16x16x32_bf16 v[50:53], v[218:221], v[166:169], v[50:53]
	v_mfma_f32_16x16x32_bf16 v[38:41], v[210:213], v[174:177], v[38:41]
	v_mfma_f32_16x16x32_bf16 v[34:37], v[218:221], v[174:177], v[34:37]
	v_mfma_f32_16x16x32_bf16 v[22:25], v[210:213], v[182:185], v[22:25]
	v_mfma_f32_16x16x32_bf16 v[18:21], v[218:221], v[182:185], v[18:21]
	v_mfma_f32_16x16x32_bf16 v[6:9], v[210:213], v[202:205], v[6:9]
	v_mfma_f32_16x16x32_bf16 v[2:5], v[218:221], v[202:205], v[2:5]
	s_setprio 0
	s_add_i32 s41, s41, 2
	s_add_u32 s18, s18, 0x100
	s_addc_u32 s19, s19, 0
	s_add_u32 s39, s39, 0x100
	s_addc_u32 s40, s40, 0
	s_cmp_gt_u32 s41, 29
	s_barrier
	s_cbranch_scc0 .LBB0_556
	s_mov_b64 s[18:19], -1
	s_cmp_gt_u32 s38, 7
	v_lshl_add_u32 v162, s0, 8, v155
	v_readlane_b32 s43, v254, 36
	v_readlane_b32 s60, v254, 37
	v_readlane_b32 s41, v254, 38
	v_readlane_b32 s40, v254, 39
	s_cbranch_scc0 .LBB0_577
	v_ashrrev_i32_e32 v163, 31, v162
	v_lshl_add_u64 v[130:131], v[162:163], 2, s[8:9]
	global_load_dword v209, v[130:131], off
	global_load_dword v208, v[130:131], off offset:64
	global_load_dword v207, v[130:131], off offset:128
	global_load_dword v206, v[130:131], off offset:192
	global_load_dword v205, v[130:131], off offset:512
	global_load_dword v204, v[130:131], off offset:576
	global_load_dword v203, v[130:131], off offset:640
	global_load_dword v202, v[130:131], off offset:704
	s_lshl_b32 s1, s38, 8
	s_ashr_i32 s18, s38, 3
	s_and_b32 s0, s38, 0xffffffd8
	s_and_b32 s11, s1, 0x700
	s_cmp_lg_u32 s0, 8
	v_add_u32_e32 v163, 0x80, v162
	s_mov_b64 s[0:1], -1
	s_cbranch_scc0 .LBB0_574
	s_mov_b64 s[22:23], -1
	s_mov_b64 s[20:21], 0
	s_cmp_lt_i32 s18, 3
	s_mov_b64 s[0:1], 0
	s_cbranch_scc1 .LBB0_569
	s_cmp_gt_i32 s18, 3
	s_cbranch_scc0 .LBB0_564
	s_cmp_eq_u32 s18, 4
	s_mov_b64 s[0:1], -1
	s_cbranch_scc0 .LBB0_563
	s_waitcnt vmcnt(0)
	v_fmamk_f32 v0, v209, 0x3a000000, v190
	v_cmp_gt_f32_e32 vcc, s78, v0
	v_mul_f32_e32 v130, 0x4b800000, v0
	v_readlane_b32 s0, v253, 19
	v_cndmask_b32_e32 v0, v0, v130, vcc
	v_rsq_f32_e32 v0, v0
	v_readlane_b32 s1, v253, 20
	s_lshl_b32 s90, s11, 1
	s_movk_i32 s13, 0x3000
	v_mul_f32_e32 v130, 0x45800000, v0
	v_cndmask_b32_e32 v0, v0, v130, vcc
	v_fmamk_f32 v130, v208, 0x3a000000, v190
	v_cmp_gt_f32_e32 vcc, s78, v130
	v_mul_f32_e32 v131, 0x4b800000, v130
	v_mov_b64_e32 v[132:133], s[0:1]
	v_cndmask_b32_e32 v130, v130, v131, vcc
	v_rsq_f32_e32 v130, v130
	v_mad_i64_i32 v[180:181], s[0:1], v162, s74, v[132:133]
	v_pk_mul_f32 v[166:167], v[128:129], v[0:1] op_sel_hi:[1,0]
	v_mul_f32_e32 v131, 0x45800000, v130
	v_cndmask_b32_e32 v144, v130, v131, vcc
	v_fmamk_f32 v130, v207, 0x3a000000, v190
	v_cmp_gt_f32_e32 vcc, s78, v130
	v_mul_f32_e32 v131, 0x4b800000, v130
	v_pk_mul_f32 v[164:165], v[126:127], v[0:1] op_sel_hi:[1,0]
	v_cndmask_b32_e32 v130, v130, v131, vcc
	v_rsq_f32_e32 v130, v130
	v_pk_mul_f32 v[168:169], v[124:125], v[0:1] op_sel_hi:[1,0]
	v_pk_mul_f32 v[170:171], v[122:123], v[0:1] op_sel_hi:[1,0]
	v_pk_mul_f32 v[172:173], v[120:121], v[0:1] op_sel_hi:[1,0]
	v_mul_f32_e32 v131, 0x45800000, v130
	v_cndmask_b32_e32 v142, v130, v131, vcc
	v_fmamk_f32 v130, v206, 0x3a000000, v190
	v_cmp_gt_f32_e32 vcc, s78, v130
	v_mul_f32_e32 v131, 0x4b800000, v130
	v_pk_mul_f32 v[174:175], v[118:119], v[0:1] op_sel_hi:[1,0]
	v_cndmask_b32_e32 v130, v130, v131, vcc
	v_rsq_f32_e32 v130, v130
	v_pk_mul_f32 v[176:177], v[116:117], v[0:1] op_sel_hi:[1,0]
	v_pk_mul_f32 v[178:179], v[114:115], v[0:1] op_sel_hi:[1,0]
;     template <int KIND>
;     __device__ __forceinline__ void body(f32x4 (&acc)[2][2][4][2], const Unit& un, int wr, int wc, int fr, int fq) const {
;     ...
;         for (int ai = 0; ai < 2; ++ai)
; #pragma unroll
;             for (int m = 0; m < 4; ++m) {
;                 const int r = rbase + ai * 128 + m * 16;
;                 const float rs = rstd[ai * 4 + m];
;                 f32x4 v[2][2];
; #pragma unroll
;                 for (int bj = 0; bj < 2; ++bj)
; #pragma unroll
;                     for (int n = 0; n < 2; ++n) v[bj][n] = acc[ai][bj][m][n] * rs;
;                 if (KIND == 0) {
;                     float* up = u + (size_t)r * D + colt + cw;
; #pragma unroll
;                     for (int bj = 0; bj < 2; ++bj)
; #pragma unroll
;                         for (int n = 0; n < 2; ++n) *(f32x4*)(up + bj * 128 + 4 * n) = v[bj][n];
;                 } else {
;                     if (KIND == 2 || KIND == 3) {
;                         const float pos = r < MS ? (float)(16384 + (r & 7)) : (float)((r - MS) % LP);
;                         const float sc = KIND == 3 ? 0.0625f : 1.0f;
; #pragma unroll
;                         for (int n = 0; n < 2; ++n)
; #pragma unroll
;                             for (int j = 0; j < 4; ++j) {
;                                 const int t = 4 * n + j; const float chi = cfv[t >> 1][(t & 1) * 2], clo = cfv[t >> 1][(t & 1) * 2 + 1];
;                                 const float pp = pos * chi, ee = fmaf(pos, chi, -pp);
;                                 const float rev = (pp - rintf(pp)) + fmaf(pos, clo, ee);
;                                 const float cc = __builtin_amdgcn_cosf(rev) * sc, ss = __builtin_amdgcn_sinf(rev) * sc;
;                                 const float t1 = v[0][n][j], t2 = v[1][n][j];
;                                 v[0][n][j] = t1 * cc - t2 * ss; v[1][n][j] = t2 * cc + t1 * ss; }
;                     } else if (KIND == 1) {
; #pragma unroll
;                         for (int bj = 0; bj < 2; ++bj)
; #pragma unroll
;                             for (int n = 0; n < 2; ++n)
; #pragma unroll
;                                 for (int j = 0; j < 4; ++j) v[bj][n][j] = siluf_(v[bj][n][j]);
;                     } else if (KIND == 5) {
; #pragma unroll
;                         for (int bj = 0; bj < 2; ++bj)
; #pragma unroll
;                             for (int n = 0; n < 2; ++n)
; #pragma unroll
	v_lshl_add_u64 v[180:181], v[180:181], 0, s[90:91]
	v_mul_f32_e32 v131, 0x45800000, v130
	v_cndmask_b32_e32 v140, v130, v131, vcc
	v_fmamk_f32 v130, v205, 0x3a000000, v190
	v_cmp_gt_f32_e32 vcc, s78, v130
	v_mul_f32_e32 v131, 0x4b800000, v130
	v_lshlrev_b32_e32 v0, 1, v154
	v_cndmask_b32_e32 v130, v130, v131, vcc
	v_rsq_f32_e32 v130, v130
	v_lshl_add_u64 v[180:181], v[180:181], 0, v[0:1]
	v_cvt_pk_bf16_f32 v164, v164, v165
	v_cvt_pk_bf16_f32 v165, v166, v167
	v_mul_f32_e32 v131, 0x45800000, v130
	v_cndmask_b32_e32 v138, v130, v131, vcc
	v_fmamk_f32 v130, v204, 0x3a000000, v190
	v_cmp_gt_f32_e32 vcc, s78, v130
	v_mul_f32_e32 v131, 0x4b800000, v130
	v_cvt_pk_bf16_f32 v166, v170, v171
	v_cvt_pk_bf16_f32 v167, v168, v169
	s_mov_b64 s[22:23], 0x3000
	v_cndmask_b32_e32 v130, v130, v131, vcc
	v_rsq_f32_e32 v130, v130
	v_lshl_add_u64 v[182:183], v[180:181], 0, s[22:23]
	v_pk_mul_f32 v[170:171], v[106:107], v[144:145] op_sel_hi:[1,0]
	v_mul_f32_e32 v131, 0x45800000, v130
	v_cndmask_b32_e32 v136, v130, v131, vcc
	v_fmamk_f32 v130, v203, 0x3a000000, v190
	v_cmp_gt_f32_e32 vcc, s78, v130
	v_mul_f32_e32 v131, 0x4b800000, v130
	s_nop 0
	v_cndmask_b32_e32 v130, v130, v131, vcc
	v_rsq_f32_e32 v130, v130
	s_nop 0
	v_mul_f32_e32 v131, 0x45800000, v130
	v_cndmask_b32_e32 v134, v130, v131, vcc
	v_fmamk_f32 v130, v202, 0x3a000000, v190
	v_cmp_gt_f32_e32 vcc, s78, v130
	v_mul_f32_e32 v131, 0x4b800000, v130
	s_nop 0
	v_cndmask_b32_e32 v130, v130, v131, vcc
	v_rsq_f32_e32 v130, v130
	s_nop 0
	v_mul_f32_e32 v131, 0x45800000, v130
	v_cndmask_b32_e32 v130, v130, v131, vcc
	v_add_co_u32_e32 v168, vcc, s13, v180
	v_or_b32_e32 v131, 16, v162
	s_nop 0
	v_addc_co_u32_e32 v169, vcc, 0, v181, vcc
	global_store_dwordx4 v[168:169], v[164:167], off
	v_pk_mul_f32 v[168:169], v[108:109], v[144:145] op_sel_hi:[1,0]
	s_nop 0
	v_cvt_pk_bf16_f32 v164, v174, v175
	v_cvt_pk_bf16_f32 v165, v172, v173
	v_cvt_pk_bf16_f32 v166, v178, v179
	v_mad_i64_i32 v[178:179], s[0:1], v131, s74, v[132:133]
	v_cvt_pk_bf16_f32 v167, v176, v177
	v_lshl_add_u64 v[178:179], v[178:179], 0, s[90:91]
	global_store_dwordx4 v[182:183], v[164:167], off offset:256
	v_lshl_add_u64 v[178:179], v[178:179], 0, v[0:1]
	v_pk_mul_f32 v[172:173], v[104:105], v[144:145] op_sel_hi:[1,0]
	v_pk_mul_f32 v[166:167], v[112:113], v[144:145] op_sel_hi:[1,0]
	v_pk_mul_f32 v[164:165], v[110:111], v[144:145] op_sel_hi:[1,0]
	v_pk_mul_f32 v[174:175], v[102:103], v[144:145] op_sel_hi:[1,0]
	v_cvt_pk_bf16_f32 v164, v164, v165
	v_cvt_pk_bf16_f32 v165, v166, v167
	v_cvt_pk_bf16_f32 v166, v170, v171
	v_cvt_pk_bf16_f32 v167, v168, v169
	v_add_co_u32_e32 v168, vcc, s13, v178
	v_pk_mul_f32 v[176:177], v[100:101], v[144:145] op_sel_hi:[1,0]
	s_nop 0
	v_addc_co_u32_e32 v169, vcc, 0, v179, vcc
	v_pk_mul_f32 v[144:145], v[98:99], v[144:145] op_sel_hi:[1,0]
	v_lshl_add_u64 v[180:181], v[178:179], 0, s[22:23]
	global_store_dwordx4 v[168:169], v[164:167], off
	v_or_b32_e32 v131, 32, v162
	v_pk_mul_f32 v[168:169], v[90:91], v[142:143] op_sel_hi:[1,0]
	v_cvt_pk_bf16_f32 v164, v174, v175
	v_cvt_pk_bf16_f32 v165, v172, v173
	v_cvt_pk_bf16_f32 v166, v144, v145
	v_cvt_pk_bf16_f32 v167, v176, v177
	global_store_dwordx4 v[180:181], v[164:167], off offset:256
	v_pk_mul_f32 v[144:145], v[96:97], v[142:143] op_sel_hi:[1,0]
	v_pk_mul_f32 v[170:171], v[88:89], v[142:143] op_sel_hi:[1,0]
	v_pk_mul_f32 v[164:165], v[94:95], v[142:143] op_sel_hi:[1,0]
	v_pk_mul_f32 v[166:167], v[92:93], v[142:143] op_sel_hi:[1,0]
	v_pk_mul_f32 v[172:173], v[86:87], v[142:143] op_sel_hi:[1,0]
	v_pk_mul_f32 v[174:175], v[84:85], v[142:143] op_sel_hi:[1,0]
	v_pk_mul_f32 v[176:177], v[82:83], v[142:143] op_sel_hi:[1,0]
	v_mad_i64_i32 v[142:143], s[0:1], v131, s74, v[132:133]
	v_lshl_add_u64 v[142:143], v[142:143], 0, s[90:91]
	v_lshl_add_u64 v[178:179], v[142:143], 0, v[0:1]
	v_cvt_pk_bf16_f32 v142, v164, v165
	v_add_co_u32_e32 v164, vcc, s13, v178
	v_cvt_pk_bf16_f32 v143, v144, v145
	v_cvt_pk_bf16_f32 v144, v168, v169
	v_cvt_pk_bf16_f32 v145, v166, v167
	v_lshl_add_u64 v[180:181], v[178:179], 0, s[22:23]
	s_nop 0
	v_addc_co_u32_e32 v165, vcc, 0, v179, vcc
	global_store_dwordx4 v[164:165], v[142:145], off
	v_or_b32_e32 v131, 48, v162
	v_pk_mul_f32 v[164:165], v[76:77], v[140:141] op_sel_hi:[1,0]
	v_cvt_pk_bf16_f32 v142, v172, v173
	v_cvt_pk_bf16_f32 v143, v170, v171
	v_cvt_pk_bf16_f32 v144, v176, v177
	v_cvt_pk_bf16_f32 v145, v174, v175
	global_store_dwordx4 v[180:181], v[142:145], off offset:256
	v_pk_mul_f32 v[166:167], v[74:75], v[140:141] op_sel_hi:[1,0]
	v_pk_mul_f32 v[168:169], v[72:73], v[140:141] op_sel_hi:[1,0]
	v_pk_mul_f32 v[142:143], v[80:81], v[140:141] op_sel_hi:[1,0]
	v_pk_mul_f32 v[144:145], v[78:79], v[140:141] op_sel_hi:[1,0]
	v_pk_mul_f32 v[170:171], v[70:71], v[140:141] op_sel_hi:[1,0]
	v_pk_mul_f32 v[172:173], v[68:69], v[140:141] op_sel_hi:[1,0]
	v_pk_mul_f32 v[174:175], v[66:67], v[140:141] op_sel_hi:[1,0]
	v_mad_i64_i32 v[140:141], s[0:1], v131, s74, v[132:133]
	v_lshl_add_u64 v[140:141], v[140:141], 0, s[90:91]
	v_lshl_add_u64 v[176:177], v[140:141], 0, v[0:1]
	v_cvt_pk_bf16_f32 v140, v144, v145
	v_add_co_u32_e32 v144, vcc, s13, v176
	v_cvt_pk_bf16_f32 v141, v142, v143
	v_cvt_pk_bf16_f32 v142, v166, v167
	v_cvt_pk_bf16_f32 v143, v164, v165
	v_lshl_add_u64 v[178:179], v[176:177], 0, s[22:23]
;     template <int KIND>
;     __device__ __forceinline__ void body(f32x4 (&acc)[2][2][4][2], const Unit& un, int wr, int wc, int fr, int fq) const {
;     ...
;         for (int ai = 0; ai < 2; ++ai)
; #pragma unroll
;             for (int m = 0; m < 4; ++m) {
;                 const int r = rbase + ai * 128 + m * 16;
;                 const float rs = rstd[ai * 4 + m];
;                 f32x4 v[2][2];
; #pragma unroll
;                 for (int bj = 0; bj < 2; ++bj)
; #pragma unroll
;                     for (int n = 0; n < 2; ++n) v[bj][n] = acc[ai][bj][m][n] * rs;
;                 if (KIND == 0) {
;                     float* up = u + (size_t)r * D + colt + cw;
; #pragma unroll
;                     for (int bj = 0; bj < 2; ++bj)
; #pragma unroll
;                         for (int n = 0; n < 2; ++n) *(f32x4*)(up + bj * 128 + 4 * n) = v[bj][n];
;                 } else {
;                     if (KIND == 2 || KIND == 3) {
;                         const float pos = r < MS ? (float)(16384 + (r & 7)) : (float)((r - MS) % LP);
;                         const float sc = KIND == 3 ? 0.0625f : 1.0f;
; #pragma unroll
;                         for (int n = 0; n < 2; ++n)
; #pragma unroll
;                             for (int j = 0; j < 4; ++j) {
;                                 const int t = 4 * n + j; const float chi = cfv[t >> 1][(t & 1) * 2], clo = cfv[t >> 1][(t & 1) * 2 + 1];
;                                 const float pp = pos * chi, ee = fmaf(pos, chi, -pp);
;                                 const float rev = (pp - rintf(pp)) + fmaf(pos, clo, ee);
;                                 const float cc = __builtin_amdgcn_cosf(rev) * sc, ss = __builtin_amdgcn_sinf(rev) * sc;
;                                 const float t1 = v[0][n][j], t2 = v[1][n][j];
;                                 v[0][n][j] = t1 * cc - t2 * ss; v[1][n][j] = t2 * cc + t1 * ss; }
;                     } else if (KIND == 1) {
; #pragma unroll
;                         for (int bj = 0; bj < 2; ++bj)
; #pragma unroll
;                             for (int n = 0; n < 2; ++n)
; #pragma unroll
;                                 for (int j = 0; j < 4; ++j) v[bj][n][j] = siluf_(v[bj][n][j]);
;                     } else if (KIND == 5) {
; #pragma unroll
;                         for (int bj = 0; bj < 2; ++bj)
; #pragma unroll
;                             for (int n = 0; n < 2; ++n)
; #pragma unroll
	s_nop 0
	v_addc_co_u32_e32 v145, vcc, 0, v177, vcc
	global_store_dwordx4 v[144:145], v[140:143], off
	v_pk_mul_f32 v[144:145], v[60:61], v[138:139] op_sel_hi:[1,0]
	v_pk_mul_f32 v[164:165], v[58:59], v[138:139] op_sel_hi:[1,0]
	v_cvt_pk_bf16_f32 v140, v170, v171
	v_cvt_pk_bf16_f32 v141, v168, v169
	v_cvt_pk_bf16_f32 v142, v174, v175
	v_cvt_pk_bf16_f32 v143, v172, v173
	global_store_dwordx4 v[178:179], v[140:143], off offset:256
	v_pk_mul_f32 v[166:167], v[56:57], v[138:139] op_sel_hi:[1,0]
	v_pk_mul_f32 v[168:169], v[54:55], v[138:139] op_sel_hi:[1,0]
	v_pk_mul_f32 v[140:141], v[64:65], v[138:139] op_sel_hi:[1,0]
	v_pk_mul_f32 v[142:143], v[62:63], v[138:139] op_sel_hi:[1,0]
	v_pk_mul_f32 v[170:171], v[52:53], v[138:139] op_sel_hi:[1,0]
	v_pk_mul_f32 v[172:173], v[50:51], v[138:139] op_sel_hi:[1,0]
	v_mad_i64_i32 v[138:139], s[0:1], v163, s74, v[132:133]
	v_lshl_add_u64 v[138:139], v[138:139], 0, s[90:91]
	v_lshl_add_u64 v[174:175], v[138:139], 0, v[0:1]
	v_cvt_pk_bf16_f32 v138, v142, v143
	v_add_co_u32_e32 v142, vcc, s13, v174
	v_cvt_pk_bf16_f32 v139, v140, v141
	v_cvt_pk_bf16_f32 v140, v164, v165
	v_cvt_pk_bf16_f32 v141, v144, v145
	v_lshl_add_u64 v[176:177], v[174:175], 0, s[22:23]
	s_nop 0
	v_addc_co_u32_e32 v143, vcc, 0, v175, vcc
	global_store_dwordx4 v[142:143], v[138:141], off
	v_add_u32_e32 v131, 0x90, v162
	v_pk_mul_f32 v[142:143], v[44:45], v[136:137] op_sel_hi:[1,0]
	v_cvt_pk_bf16_f32 v138, v168, v169
	v_cvt_pk_bf16_f32 v139, v166, v167
	v_cvt_pk_bf16_f32 v140, v172, v173
	v_cvt_pk_bf16_f32 v141, v170, v171
	global_store_dwordx4 v[176:177], v[138:141], off offset:256
	v_pk_mul_f32 v[144:145], v[42:43], v[136:137] op_sel_hi:[1,0]
	v_pk_mul_f32 v[164:165], v[40:41], v[136:137] op_sel_hi:[1,0]
	v_pk_mul_f32 v[138:139], v[48:49], v[136:137] op_sel_hi:[1,0]
	v_pk_mul_f32 v[140:141], v[46:47], v[136:137] op_sel_hi:[1,0]
	v_pk_mul_f32 v[166:167], v[38:39], v[136:137] op_sel_hi:[1,0]
	v_pk_mul_f32 v[168:169], v[36:37], v[136:137] op_sel_hi:[1,0]
	v_pk_mul_f32 v[170:171], v[34:35], v[136:137] op_sel_hi:[1,0]
	v_mad_i64_i32 v[136:137], s[0:1], v131, s74, v[132:133]
	v_lshl_add_u64 v[136:137], v[136:137], 0, s[90:91]
	v_lshl_add_u64 v[172:173], v[136:137], 0, v[0:1]
	v_cvt_pk_bf16_f32 v136, v140, v141
	v_add_co_u32_e32 v140, vcc, s13, v172
	v_cvt_pk_bf16_f32 v137, v138, v139
	v_cvt_pk_bf16_f32 v138, v144, v145
	v_cvt_pk_bf16_f32 v139, v142, v143
	v_lshl_add_u64 v[174:175], v[172:173], 0, s[22:23]
	s_nop 0
	v_addc_co_u32_e32 v141, vcc, 0, v173, vcc
	global_store_dwordx4 v[140:141], v[136:139], off
	v_add_u32_e32 v131, 0xa0, v162
	v_pk_mul_f32 v[140:141], v[28:29], v[134:135] op_sel_hi:[1,0]
	v_cvt_pk_bf16_f32 v136, v166, v167
	v_cvt_pk_bf16_f32 v137, v164, v165
	v_cvt_pk_bf16_f32 v138, v170, v171
	v_cvt_pk_bf16_f32 v139, v168, v169
	global_store_dwordx4 v[174:175], v[136:139], off offset:256
	v_pk_mul_f32 v[142:143], v[26:27], v[134:135] op_sel_hi:[1,0]
	v_pk_mul_f32 v[144:145], v[24:25], v[134:135] op_sel_hi:[1,0]
	v_pk_mul_f32 v[136:137], v[32:33], v[134:135] op_sel_hi:[1,0]
	v_pk_mul_f32 v[138:139], v[30:31], v[134:135] op_sel_hi:[1,0]
	v_pk_mul_f32 v[164:165], v[22:23], v[134:135] op_sel_hi:[1,0]
	v_pk_mul_f32 v[166:167], v[20:21], v[134:135] op_sel_hi:[1,0]
	v_pk_mul_f32 v[168:169], v[18:19], v[134:135] op_sel_hi:[1,0]
	v_mad_i64_i32 v[134:135], s[0:1], v131, s74, v[132:133]
	v_lshl_add_u64 v[134:135], v[134:135], 0, s[90:91]
	v_lshl_add_u64 v[170:171], v[134:135], 0, v[0:1]
	v_cvt_pk_bf16_f32 v134, v138, v139
	v_add_co_u32_e32 v138, vcc, s13, v170
	v_cvt_pk_bf16_f32 v135, v136, v137
	v_cvt_pk_bf16_f32 v136, v142, v143
	v_cvt_pk_bf16_f32 v137, v140, v141
	v_lshl_add_u64 v[172:173], v[170:171], 0, s[22:23]
	s_nop 0
	v_addc_co_u32_e32 v139, vcc, 0, v171, vcc
	global_store_dwordx4 v[138:139], v[134:137], off
	v_pk_mul_f32 v[138:139], v[12:13], v[130:131] op_sel_hi:[1,0]
	v_pk_mul_f32 v[140:141], v[10:11], v[130:131] op_sel_hi:[1,0]
	v_cvt_pk_bf16_f32 v134, v164, v165
	v_cvt_pk_bf16_f32 v135, v144, v145
	v_cvt_pk_bf16_f32 v136, v168, v169
	v_cvt_pk_bf16_f32 v137, v166, v167
	global_store_dwordx4 v[172:173], v[134:137], off offset:256
	v_pk_mul_f32 v[142:143], v[8:9], v[130:131] op_sel_hi:[1,0]
	v_pk_mul_f32 v[144:145], v[6:7], v[130:131] op_sel_hi:[1,0]
	v_pk_mul_f32 v[134:135], v[16:17], v[130:131] op_sel_hi:[1,0]
	v_pk_mul_f32 v[136:137], v[14:15], v[130:131] op_sel_hi:[1,0]
	v_pk_mul_f32 v[164:165], v[4:5], v[130:131] op_sel_hi:[1,0]
	v_pk_mul_f32 v[166:167], v[2:3], v[130:131] op_sel_hi:[1,0]
	v_add_u32_e32 v130, 0xb0, v162
	v_mad_i64_i32 v[130:131], s[0:1], v130, s74, v[132:133]
	v_lshl_add_u64 v[130:131], v[130:131], 0, s[90:91]
	v_lshl_add_u64 v[168:169], v[130:131], 0, v[0:1]
	v_cvt_pk_bf16_f32 v130, v136, v137
	v_cvt_pk_bf16_f32 v131, v134, v135
	v_add_co_u32_e32 v134, vcc, s13, v168
	v_lshl_add_u64 v[170:171], v[168:169], 0, s[22:23]
	v_cvt_pk_bf16_f32 v132, v140, v141
	v_cvt_pk_bf16_f32 v133, v138, v139
	s_nop 0
	v_addc_co_u32_e32 v135, vcc, 0, v169, vcc
	global_store_dwordx4 v[134:135], v[130:133], off
	s_mov_b64 s[0:1], 0
	s_nop 0
	v_cvt_pk_bf16_f32 v130, v144, v145
	v_cvt_pk_bf16_f32 v131, v142, v143
	v_cvt_pk_bf16_f32 v132, v166, v167
	v_cvt_pk_bf16_f32 v133, v164, v165
	global_store_dwordx4 v[170:171], v[130:133], off offset:256

; #define LAS __attribute__((address_space(3)))
; __device__ __forceinline__ int launder(int v) { asm volatile("" : "+v"(v)); return v; }
; __device__ __forceinline__ void tr_tile(LAS float* tile, const float* src, int N, bf16_t* dst, int Kd, int k0, int n0, const float* scale, const float* nscale, int tid) {
;     constexpr int P = 257;
;     f32x4 v[8];
; #pragma unroll
;     for (int i = 0; i < 8; ++i) { const int idx4 = i * 512 + tid, r = idx4 >> 6, c4 = (idx4 & 63) * 4;
;         v[i] = __builtin_nontemporal_load((const f32x4*)(src + (size_t)(k0 + r) * N + n0 + c4)); }
; __device__ void phase0(const Params& p, LAS unsigned char* lds, const int tid_in, const int bid) {
;     const int tid = launder(tid_in);
;     const int wid = tid >> 6, lane = tid & 63;
;     constexpr int NT_L = 2880, NROWI = MPAD / 8;
;     if (bid == 0 && tid < 128) {
;         const float invf = powf(10000.0f, -(float)tid / 128.0f);
;         const double c = (double)invf * 0.15915494309189535;
;         const float hi = (float)c, lo = (float)(c - (double)hi);
;         float* cf = (float*)(pws(p) + OFF_CS) + tid * 2; cf[0] = hi; cf[1] = lo;
;     }
;     for (int it = bid; it < NT_L + NROWI; it += gridDim.x) {
;         if (it < NT_L) {
;             conv_item(p, 0, it, lds, tid);
.LBB0_585:
	s_or_b64 exec, exec, s[0:1]
	s_cmpk_gt_i32 s82, 0xfdf
	s_cbranch_scc1 .LBB0_660
	s_waitcnt vmcnt(0)
	v_lshlrev_b32_e32 v2, 2, v244
	v_add_u32_e32 v4, 0x200, v244
	v_add_u32_e32 v5, 0x400, v244
	v_add_u32_e32 v6, 0x600, v244
	v_add_u32_e32 v7, 0x800, v244
	v_add_u32_e32 v8, 0xa00, v244
	v_add_u32_e32 v9, 0xc00, v244
	v_add_u32_e32 v10, 0xe00, v244
	v_ashrrev_i32_e32 v39, 6, v244
	v_and_b32_e32 v40, 0xfc, v2
	v_ashrrev_i32_e32 v43, 6, v4
	v_ashrrev_i32_e32 v74, 6, v5
	v_ashrrev_i32_e32 v75, 6, v6
	v_ashrrev_i32_e32 v76, 6, v7
	v_ashrrev_i32_e32 v77, 6, v8
	v_ashrrev_i32_e32 v78, 6, v9
	v_ashrrev_i32_e32 v79, 6, v10
	s_movk_i32 s0, 0x404
	v_and_b32_e32 v42, 60, v2
	v_and_b32_e32 v3, 63, v244
	v_lshlrev_b32_e32 v0, 2, v40
	v_mul_lo_u32 v81, v39, s0
	v_mul_lo_u32 v82, v43, s0
	v_mul_lo_u32 v83, v74, s0
	v_mul_lo_u32 v84, v75, s0
	v_mul_lo_u32 v85, v76, s0
	v_mul_lo_u32 v86, v77, s0
	v_mul_lo_u32 v87, v78, s0
	v_mul_lo_u32 v88, v79, s0
	v_mad_u32_u24 v2, v42, s0, 0
	v_readlane_b32 s0, v254, 20
	v_lshlrev_b32_e32 v38, 2, v3
	v_add_u32_e32 v80, 0, v0
	v_ashrrev_i32_e32 v89, 4, v244
	v_ashrrev_i32_e32 v91, 4, v4
	v_ashrrev_i32_e32 v93, 4, v5
	v_ashrrev_i32_e32 v95, 4, v6
	v_ashrrev_i32_e32 v97, 4, v7
	v_ashrrev_i32_e32 v99, 4, v8
	v_ashrrev_i32_e32 v101, 4, v9
	v_ashrrev_i32_e32 v103, 4, v10
	v_lshl_add_u64 v[44:45], s[56:57], 0, v[0:1]
	v_lshlrev_b32_e32 v0, 1, v42
	v_readlane_b32 s1, v254, 21
	v_lshl_add_u32 v90, v89, 2, v2
	v_lshl_add_u32 v92, v91, 2, v2
	v_lshl_add_u32 v94, v93, 2, v2
	v_lshl_add_u32 v96, v95, 2, v2
	v_lshl_add_u32 v98, v97, 2, v2
	v_lshl_add_u32 v100, v99, 2, v2
	v_lshl_add_u32 v102, v101, 2, v2
	v_lshl_add_u32 v104, v103, 2, v2
	v_or_b32_e32 v2, 0x400, v38
	v_or_b32_e32 v4, 0x500, v38
	v_or_b32_e32 v6, 0x600, v38
	v_or_b32_e32 v8, 0x700, v38
	v_lshl_add_u64 v[46:47], s[0:1], 0, v[0:1]
	v_lshlrev_b32_e32 v0, 3, v3
	v_add_u32_e32 v41, 0xffffa600, v39
	v_cmp_eq_u32_e64 s[6:7], 0, v3
	v_lshl_add_u64 v[48:49], s[68:69], 0, v[0:1]
	s_cmpk_lg_u32 s42, 0x100
	s_cbranch_scc1 .Lp0_fwd0
	s_bitcmp1_b32 s82, 3
	s_cbranch_scc0 .Lp0_fwd0
	s_sub_i32 s0, 0xfdf, s82
	s_andn2_b32 s0, s0, 0xff
	s_add_i32 s82, s82, s0
.Lp0_fwd0:
	s_lshl_b32 s12, s82, 3
	s_lshl_b32 s13, s82, 8
	s_lshl_b32 s14, s82, 5
	v_lshlrev_b32_e32 v50, 2, v2
	v_lshlrev_b32_e32 v52, 2, v4
	v_lshlrev_b32_e32 v54, 2, v6
	v_lshlrev_b32_e32 v56, 2, v8
	s_branch .LBB0_591

; __device__ void phase0(const Params& p, LAS unsigned char* lds, const int tid_in, const int bid) {
;     ...
;     for (int it = bid; it < NT_L + NROWI; it += gridDim.x) {
;         if (it < NT_L) {
;             conv_item(p, 0, it, lds, tid);
.LBB0_590:
	s_cmpk_lg_u32 s42, 0x100
	s_cbranch_scc1 .Lp0_fwd1
	s_bitcmp1_b32 s82, 3
	s_cbranch_scc0 .Lp0_fwd1
	v_readlane_b32 s0, v254, 25
	s_nop 0
	s_sub_i32 s12, s12, s0
	v_readlane_b32 s0, v254, 27
	s_nop 0
	s_sub_i32 s13, s13, s0
	v_readlane_b32 s0, v254, 29
	s_nop 0
	s_sub_i32 s14, s14, s0
	s_sub_i32 s82, s82, s42
	s_cmp_lt_i32 s82, 0
	s_cbranch_scc1 .LBB0_660
	s_branch .LBB0_591
